# adds: proj gated-sum: 6 of 16 gate quads per thread stay in spare VGPRs between the gate unit and the branch unit (no global round trip)
# speedup vs baseline: 1.0376x; 1.0047x over previous
; __device__ __forceinline__ unsigned cvt_pk_bf16(float lo, float hi) { const f32x2 v = {lo, hi}; const bf16x2_t b = __builtin_convertvector(v, bf16x2_t); return __builtin_bit_cast(unsigned, b); }
; __device__ __forceinline__ float bf_lo(unsigned u) { return __uint_as_float(u << 16); }
; __device__ __forceinline__ float bf_hi(unsigned u) { return __uint_as_float(u & 0xffff0000u); }
;     __device__ __forceinline__ void operator()(const f32x4 (&acc)[2][2][4][2], const Unit& u, int wr, int wc, int fr, int fq) const {
;     ...
;         for (int ai = 0; ai < 2; ++ai)
; #pragma unroll
;             for (int bj = 0; bj < 2; ++bj)
; #pragma unroll
;                 for (int m = 0; m < 4; ++m) {
;                     const u32x4 g = *((const u32x4*)Gs + ((size_t)(tile * 16 + (ai * 2 + bj) * 4 + m) * NTHREADS + tid));
;                     f32x4 y0 = acc[ai][bj][m][0], y1 = acc[ai][bj][m][1];
;                     y0[0] *= bf_lo(g.x); y0[1] *= bf_hi(g.x); y0[2] *= bf_lo(g.y); y0[3] *= bf_hi(g.y);
;                     y1[0] *= bf_lo(g.z); y1[1] *= bf_hi(g.z); y1[2] *= bf_lo(g.w); y1[3] *= bf_hi(g.w);
;                     u32x4* sp = (u32x4*)Sb + ((size_t)(tile * 16 + (ai * 2 + bj) * 4 + m) * NTHREADS + tid);
;                     if (br != 0) { const u32x4 t = *sp;
;                         y0[0] += bf_lo(t.x); y0[1] += bf_hi(t.x); y0[2] += bf_lo(t.y); y0[3] += bf_hi(t.y); y1[0] += bf_lo(t.z); y1[1] += bf_hi(t.z); y1[2] += bf_lo(t.w); y1[3] += bf_hi(t.w); }
;                     u32x4 w; w.x = cvt_pk_bf16(y0[0], y0[1]); w.y = cvt_pk_bf16(y0[2], y0[3]); w.z = cvt_pk_bf16(y1[0], y1[1]); w.w = cvt_pk_bf16(y1[2], y1[3]);
;                     if (br != 2) *sp = w;
;                     else {
;                         *(u32x4*)(MIXPRE + (size_t)(row0 + ai * 128 + m * 16) * DM + col00 + bj * 128) = w; }
.LBB0_305:
	s_lshl_b32 s12, s18, 4
	s_lshl_b32 s13, s12, 9
	v_add_u32_e32 v166, s13, v144
	v_lshlrev_b32_e32 v166, 4, v166
	v_lshl_add_u32 v226, s20, 8, v170
	v_lshlrev_b32_e32 v226, 11, v226
	v_lshl_add_u32 v226, v134, 1, v226
	s_mov_b64 s[12:13], s[14:15]
	s_mov_b64 s[20:21], s[34:35]
	s_mov_b64 s[44:45], s[34:35]
	s_cmp_eq_u32 s19, 0
	s_cbranch_scc1 .Lpl_br0
	s_cmp_eq_u32 s19, 1
	s_cbranch_scc1 .Lpl_br1
	s_add_u32 s12, s12, 0x2000
	s_addc_u32 s13, s13, 0
	global_load_dwordx4 v[182:185], v166, s[20:21]
	s_add_u32 s20, s20, 0x2000
	s_addc_u32 s21, s21, 0
	s_add_u32 s12, s12, 0x2000
	s_addc_u32 s13, s13, 0
	global_load_dwordx4 v[186:189], v166, s[20:21]
	s_add_u32 s20, s20, 0x2000
	s_addc_u32 s21, s21, 0
	s_add_u32 s12, s12, 0x2000
	s_addc_u32 s13, s13, 0
	global_load_dwordx4 v[202:205], v166, s[20:21]
	s_add_u32 s20, s20, 0x2000
	s_addc_u32 s21, s21, 0
	s_add_u32 s12, s12, 0x2000
	s_addc_u32 s13, s13, 0
	global_load_dwordx4 v[206:209], v166, s[20:21]
	s_add_u32 s20, s20, 0x2000
	s_addc_u32 s21, s21, 0
	s_add_u32 s12, s12, 0x2000
	s_addc_u32 s13, s13, 0
	global_load_dwordx4 v[210:213], v166, s[20:21]
	s_add_u32 s20, s20, 0x2000
	s_addc_u32 s21, s21, 0
	s_waitcnt vmcnt(4)
	v_lshlrev_b32_e32 v224, 16, v230
	v_and_b32_e32 v225, 0xffff0000, v230
	v_mul_f32_e32 v132, v126, v224
	v_mul_f32_e32 v133, v127, v225
	v_lshlrev_b32_e32 v224, 16, v231
	v_and_b32_e32 v225, 0xffff0000, v231
	v_mul_f32_e32 v164, v128, v224
	v_mul_f32_e32 v165, v129, v225
	v_lshlrev_b32_e32 v224, 16, v232
	v_and_b32_e32 v225, 0xffff0000, v232
	v_mul_f32_e32 v168, v122, v224
	v_mul_f32_e32 v169, v123, v225
	v_lshlrev_b32_e32 v224, 16, v233
	v_and_b32_e32 v225, 0xffff0000, v233
	v_mul_f32_e32 v222, v124, v224
	v_mul_f32_e32 v223, v125, v225
	v_lshlrev_b32_e32 v224, 16, v182
	v_and_b32_e32 v225, 0xffff0000, v182
	v_add_f32_e32 v132, v132, v224
	v_add_f32_e32 v133, v133, v225
	v_lshlrev_b32_e32 v224, 16, v183
	v_and_b32_e32 v225, 0xffff0000, v183
	v_add_f32_e32 v164, v164, v224
	v_add_f32_e32 v165, v165, v225
	v_lshlrev_b32_e32 v224, 16, v184
	v_and_b32_e32 v225, 0xffff0000, v184
	v_add_f32_e32 v168, v168, v224
	v_add_f32_e32 v169, v169, v225
	v_lshlrev_b32_e32 v224, 16, v185
	v_and_b32_e32 v225, 0xffff0000, v185
	v_add_f32_e32 v222, v222, v224
	v_add_f32_e32 v223, v223, v225
	v_cvt_pk_bf16_f32 v214, v132, v133
	v_cvt_pk_bf16_f32 v215, v164, v165
	v_cvt_pk_bf16_f32 v216, v168, v169
	v_cvt_pk_bf16_f32 v217, v222, v223
	s_add_u32 s44, s48, 0x0
	s_addc_u32 s45, s49, 0
	global_store_dwordx4 v226, v[214:217], s[44:45]
	s_add_u32 s12, s12, 0x2000
	s_addc_u32 s13, s13, 0
	global_load_dwordx4 v[182:185], v166, s[20:21]
	s_add_u32 s20, s20, 0x2000
	s_addc_u32 s21, s21, 0
	s_waitcnt vmcnt(5)
	v_lshlrev_b32_e32 v224, 16, v234
	v_and_b32_e32 v225, 0xffff0000, v234
	v_mul_f32_e32 v132, v118, v224
	v_mul_f32_e32 v133, v119, v225
	v_lshlrev_b32_e32 v224, 16, v235
	v_and_b32_e32 v225, 0xffff0000, v235
	v_mul_f32_e32 v164, v120, v224
	v_mul_f32_e32 v165, v121, v225
	v_lshlrev_b32_e32 v224, 16, v236
	v_and_b32_e32 v225, 0xffff0000, v236
	v_mul_f32_e32 v168, v114, v224
	v_mul_f32_e32 v169, v115, v225
	v_lshlrev_b32_e32 v224, 16, v237
	v_and_b32_e32 v225, 0xffff0000, v237
	v_mul_f32_e32 v222, v116, v224
	v_mul_f32_e32 v223, v117, v225
	v_lshlrev_b32_e32 v224, 16, v186
	v_and_b32_e32 v225, 0xffff0000, v186
	v_add_f32_e32 v132, v132, v224
	v_add_f32_e32 v133, v133, v225
	v_lshlrev_b32_e32 v224, 16, v187
	v_and_b32_e32 v225, 0xffff0000, v187
	v_add_f32_e32 v164, v164, v224
	v_add_f32_e32 v165, v165, v225
	v_lshlrev_b32_e32 v224, 16, v188
	v_and_b32_e32 v225, 0xffff0000, v188
	v_add_f32_e32 v168, v168, v224
	v_add_f32_e32 v169, v169, v225
	v_lshlrev_b32_e32 v224, 16, v189
	v_and_b32_e32 v225, 0xffff0000, v189
	v_add_f32_e32 v222, v222, v224
	v_add_f32_e32 v223, v223, v225
	v_cvt_pk_bf16_f32 v218, v132, v133
	v_cvt_pk_bf16_f32 v219, v164, v165
	v_cvt_pk_bf16_f32 v220, v168, v169
	v_cvt_pk_bf16_f32 v221, v222, v223
	s_add_u32 s44, s48, 0x8000
	s_addc_u32 s45, s49, 0
	global_store_dwordx4 v226, v[218:221], s[44:45]
	global_load_dwordx4 v[156:159], v166, s[12:13]
	s_add_u32 s12, s12, 0x2000
	s_addc_u32 s13, s13, 0
	global_load_dwordx4 v[186:189], v166, s[20:21]
	s_add_u32 s20, s20, 0x2000
	s_addc_u32 s21, s21, 0
	s_waitcnt vmcnt(7)
	v_lshlrev_b32_e32 v224, 16, v238
	v_and_b32_e32 v225, 0xffff0000, v238
	v_mul_f32_e32 v132, v110, v224
	v_mul_f32_e32 v133, v111, v225
	v_lshlrev_b32_e32 v224, 16, v239
	v_and_b32_e32 v225, 0xffff0000, v239
	v_mul_f32_e32 v164, v112, v224
	v_mul_f32_e32 v165, v113, v225
	v_lshlrev_b32_e32 v224, 16, v240
	v_and_b32_e32 v225, 0xffff0000, v240
	v_mul_f32_e32 v168, v106, v224
	v_mul_f32_e32 v169, v107, v225
	v_lshlrev_b32_e32 v224, 16, v241
	v_and_b32_e32 v225, 0xffff0000, v241
	v_mul_f32_e32 v222, v108, v224
	v_mul_f32_e32 v223, v109, v225
	v_lshlrev_b32_e32 v224, 16, v202
	v_and_b32_e32 v225, 0xffff0000, v202
	v_add_f32_e32 v132, v132, v224
	v_add_f32_e32 v133, v133, v225
	v_lshlrev_b32_e32 v224, 16, v203
	v_and_b32_e32 v225, 0xffff0000, v203
	v_add_f32_e32 v164, v164, v224
	v_add_f32_e32 v165, v165, v225
	v_lshlrev_b32_e32 v224, 16, v204
	v_and_b32_e32 v225, 0xffff0000, v204
	v_add_f32_e32 v168, v168, v224
	v_add_f32_e32 v169, v169, v225
	v_lshlrev_b32_e32 v224, 16, v205
	v_and_b32_e32 v225, 0xffff0000, v205
	v_add_f32_e32 v222, v222, v224
	v_add_f32_e32 v223, v223, v225
	v_cvt_pk_bf16_f32 v214, v132, v133
	v_cvt_pk_bf16_f32 v215, v164, v165
	v_cvt_pk_bf16_f32 v216, v168, v169
	v_cvt_pk_bf16_f32 v217, v222, v223
	s_add_u32 s44, s48, 0x10000
	s_addc_u32 s45, s49, 0
	global_store_dwordx4 v226, v[214:217], s[44:45]
	global_load_dwordx4 v[160:163], v166, s[12:13]
	s_add_u32 s12, s12, 0x2000
	s_addc_u32 s13, s13, 0
	global_load_dwordx4 v[202:205], v166, s[20:21]
	s_add_u32 s20, s20, 0x2000
	s_addc_u32 s21, s21, 0
	s_waitcnt vmcnt(9)
; __device__ __forceinline__ unsigned cvt_pk_bf16(float lo, float hi) { const f32x2 v = {lo, hi}; const bf16x2_t b = __builtin_convertvector(v, bf16x2_t); return __builtin_bit_cast(unsigned, b); }
; __device__ __forceinline__ float bf_lo(unsigned u) { return __uint_as_float(u << 16); }
; __device__ __forceinline__ float bf_hi(unsigned u) { return __uint_as_float(u & 0xffff0000u); }
;     __device__ __forceinline__ void operator()(const f32x4 (&acc)[2][2][4][2], const Unit& u, int wr, int wc, int fr, int fq) const {
;     ...
;         for (int ai = 0; ai < 2; ++ai)
; #pragma unroll
;             for (int bj = 0; bj < 2; ++bj)
; #pragma unroll
;                 for (int m = 0; m < 4; ++m) {
;                     const u32x4 g = *((const u32x4*)Gs + ((size_t)(tile * 16 + (ai * 2 + bj) * 4 + m) * NTHREADS + tid));
;                     f32x4 y0 = acc[ai][bj][m][0], y1 = acc[ai][bj][m][1];
;                     y0[0] *= bf_lo(g.x); y0[1] *= bf_hi(g.x); y0[2] *= bf_lo(g.y); y0[3] *= bf_hi(g.y);
;                     y1[0] *= bf_lo(g.z); y1[1] *= bf_hi(g.z); y1[2] *= bf_lo(g.w); y1[3] *= bf_hi(g.w);
;                     u32x4* sp = (u32x4*)Sb + ((size_t)(tile * 16 + (ai * 2 + bj) * 4 + m) * NTHREADS + tid);
;                     if (br != 0) { const u32x4 t = *sp;
;                         y0[0] += bf_lo(t.x); y0[1] += bf_hi(t.x); y0[2] += bf_lo(t.y); y0[3] += bf_hi(t.y); y1[0] += bf_lo(t.z); y1[1] += bf_hi(t.z); y1[2] += bf_lo(t.w); y1[3] += bf_hi(t.w); }
;                     u32x4 w; w.x = cvt_pk_bf16(y0[0], y0[1]); w.y = cvt_pk_bf16(y0[2], y0[3]); w.z = cvt_pk_bf16(y1[0], y1[1]); w.w = cvt_pk_bf16(y1[2], y1[3]);
;                     if (br != 2) *sp = w;
;                     else {
;                         *(u32x4*)(MIXPRE + (size_t)(row0 + ai * 128 + m * 16) * DM + col00 + bj * 128) = w; }
	v_lshlrev_b32_e32 v224, 16, v242
	v_and_b32_e32 v225, 0xffff0000, v242
	v_mul_f32_e32 v132, v102, v224
	v_mul_f32_e32 v133, v103, v225
	v_lshlrev_b32_e32 v224, 16, v243
	v_and_b32_e32 v225, 0xffff0000, v243
	v_mul_f32_e32 v164, v104, v224
	v_mul_f32_e32 v165, v105, v225
	v_lshlrev_b32_e32 v224, 16, v244
	v_and_b32_e32 v225, 0xffff0000, v244
	v_mul_f32_e32 v168, v98, v224
	v_mul_f32_e32 v169, v99, v225
	v_lshlrev_b32_e32 v224, 16, v245
	v_and_b32_e32 v225, 0xffff0000, v245
	v_mul_f32_e32 v222, v100, v224
	v_mul_f32_e32 v223, v101, v225
	v_lshlrev_b32_e32 v224, 16, v206
	v_and_b32_e32 v225, 0xffff0000, v206
	v_add_f32_e32 v132, v132, v224
	v_add_f32_e32 v133, v133, v225
	v_lshlrev_b32_e32 v224, 16, v207
	v_and_b32_e32 v225, 0xffff0000, v207
	v_add_f32_e32 v164, v164, v224
	v_add_f32_e32 v165, v165, v225
	v_lshlrev_b32_e32 v224, 16, v208
	v_and_b32_e32 v225, 0xffff0000, v208
	v_add_f32_e32 v168, v168, v224
	v_add_f32_e32 v169, v169, v225
	v_lshlrev_b32_e32 v224, 16, v209
	v_and_b32_e32 v225, 0xffff0000, v209
	v_add_f32_e32 v222, v222, v224
	v_add_f32_e32 v223, v223, v225
	v_cvt_pk_bf16_f32 v218, v132, v133
	v_cvt_pk_bf16_f32 v219, v164, v165
	v_cvt_pk_bf16_f32 v220, v168, v169
	v_cvt_pk_bf16_f32 v221, v222, v223
	s_add_u32 s44, s48, 0x18000
	s_addc_u32 s45, s49, 0
	global_store_dwordx4 v226, v[218:221], s[44:45]
	global_load_dwordx4 v[174:177], v166, s[12:13]
	s_add_u32 s12, s12, 0x2000
	s_addc_u32 s13, s13, 0
	global_load_dwordx4 v[206:209], v166, s[20:21]
	s_add_u32 s20, s20, 0x2000
	s_addc_u32 s21, s21, 0
	s_waitcnt vmcnt(11)
	v_lshlrev_b32_e32 v224, 16, v246
	v_and_b32_e32 v225, 0xffff0000, v246
	v_mul_f32_e32 v132, v62, v224
	v_mul_f32_e32 v133, v63, v225
	v_lshlrev_b32_e32 v224, 16, v247
	v_and_b32_e32 v225, 0xffff0000, v247
	v_mul_f32_e32 v164, v64, v224
	v_mul_f32_e32 v165, v65, v225
	v_lshlrev_b32_e32 v224, 16, v248
	v_and_b32_e32 v225, 0xffff0000, v248
	v_mul_f32_e32 v168, v58, v224
	v_mul_f32_e32 v169, v59, v225
	v_lshlrev_b32_e32 v224, 16, v249
	v_and_b32_e32 v225, 0xffff0000, v249
	v_mul_f32_e32 v222, v60, v224
	v_mul_f32_e32 v223, v61, v225
	v_lshlrev_b32_e32 v224, 16, v210
	v_and_b32_e32 v225, 0xffff0000, v210
	v_add_f32_e32 v132, v132, v224
	v_add_f32_e32 v133, v133, v225
	v_lshlrev_b32_e32 v224, 16, v211
	v_and_b32_e32 v225, 0xffff0000, v211
	v_add_f32_e32 v164, v164, v224
	v_add_f32_e32 v165, v165, v225
	v_lshlrev_b32_e32 v224, 16, v212
	v_and_b32_e32 v225, 0xffff0000, v212
	v_add_f32_e32 v168, v168, v224
	v_add_f32_e32 v169, v169, v225
	v_lshlrev_b32_e32 v224, 16, v213
	v_and_b32_e32 v225, 0xffff0000, v213
	v_add_f32_e32 v222, v222, v224
	v_add_f32_e32 v223, v223, v225
	v_cvt_pk_bf16_f32 v214, v132, v133
	v_cvt_pk_bf16_f32 v215, v164, v165
	v_cvt_pk_bf16_f32 v216, v168, v169
	v_cvt_pk_bf16_f32 v217, v222, v223
	s_add_u32 s44, s48, 0x100
	s_addc_u32 s45, s49, 0
	global_store_dwordx4 v226, v[214:217], s[44:45]
	global_load_dwordx4 v[178:181], v166, s[12:13]
	s_add_u32 s12, s12, 0x2000
	s_addc_u32 s13, s13, 0
	global_load_dwordx4 v[210:213], v166, s[20:21]
	s_add_u32 s20, s20, 0x2000
	s_addc_u32 s21, s21, 0
	s_waitcnt vmcnt(12)
	v_lshlrev_b32_e32 v224, 16, v198
	v_and_b32_e32 v225, 0xffff0000, v198
	v_mul_f32_e32 v132, v54, v224
	v_mul_f32_e32 v133, v55, v225
	v_lshlrev_b32_e32 v224, 16, v199
	v_and_b32_e32 v225, 0xffff0000, v199
	v_mul_f32_e32 v164, v56, v224
	v_mul_f32_e32 v165, v57, v225
	v_lshlrev_b32_e32 v224, 16, v200
	v_and_b32_e32 v225, 0xffff0000, v200
	v_mul_f32_e32 v168, v50, v224
	v_mul_f32_e32 v169, v51, v225
	v_lshlrev_b32_e32 v224, 16, v201
	v_and_b32_e32 v225, 0xffff0000, v201
	v_mul_f32_e32 v222, v52, v224
	v_mul_f32_e32 v223, v53, v225
	v_lshlrev_b32_e32 v224, 16, v182
	v_and_b32_e32 v225, 0xffff0000, v182
	v_add_f32_e32 v132, v132, v224
	v_add_f32_e32 v133, v133, v225
	v_lshlrev_b32_e32 v224, 16, v183
	v_and_b32_e32 v225, 0xffff0000, v183
	v_add_f32_e32 v164, v164, v224
	v_add_f32_e32 v165, v165, v225
	v_lshlrev_b32_e32 v224, 16, v184
	v_and_b32_e32 v225, 0xffff0000, v184
	v_add_f32_e32 v168, v168, v224
	v_add_f32_e32 v169, v169, v225
	v_lshlrev_b32_e32 v224, 16, v185
	v_and_b32_e32 v225, 0xffff0000, v185
	v_add_f32_e32 v222, v222, v224
	v_add_f32_e32 v223, v223, v225
	v_cvt_pk_bf16_f32 v218, v132, v133
	v_cvt_pk_bf16_f32 v219, v164, v165
	v_cvt_pk_bf16_f32 v220, v168, v169
	v_cvt_pk_bf16_f32 v221, v222, v223
	s_add_u32 s44, s48, 0x8100
	s_addc_u32 s45, s49, 0
	global_store_dwordx4 v226, v[218:221], s[44:45]
	global_load_dwordx4 v[152:155], v166, s[12:13]
	s_add_u32 s12, s12, 0x2000
	s_addc_u32 s13, s13, 0
	global_load_dwordx4 v[182:185], v166, s[20:21]
	s_add_u32 s20, s20, 0x2000
	s_addc_u32 s21, s21, 0
	s_waitcnt vmcnt(12)
	v_lshlrev_b32_e32 v224, 16, v156
	v_and_b32_e32 v225, 0xffff0000, v156
	v_mul_f32_e32 v132, v46, v224
	v_mul_f32_e32 v133, v47, v225
	v_lshlrev_b32_e32 v224, 16, v157
	v_and_b32_e32 v225, 0xffff0000, v157
	v_mul_f32_e32 v164, v48, v224
	v_mul_f32_e32 v165, v49, v225
	v_lshlrev_b32_e32 v224, 16, v158
	v_and_b32_e32 v225, 0xffff0000, v158
	v_mul_f32_e32 v168, v42, v224
	v_mul_f32_e32 v169, v43, v225
	v_lshlrev_b32_e32 v224, 16, v159
	v_and_b32_e32 v225, 0xffff0000, v159
	v_mul_f32_e32 v222, v44, v224
	v_mul_f32_e32 v223, v45, v225
	v_lshlrev_b32_e32 v224, 16, v186
	v_and_b32_e32 v225, 0xffff0000, v186
	v_add_f32_e32 v132, v132, v224
	v_add_f32_e32 v133, v133, v225
	v_lshlrev_b32_e32 v224, 16, v187
	v_and_b32_e32 v225, 0xffff0000, v187
	v_add_f32_e32 v164, v164, v224
	v_add_f32_e32 v165, v165, v225
	v_lshlrev_b32_e32 v224, 16, v188
	v_and_b32_e32 v225, 0xffff0000, v188
	v_add_f32_e32 v168, v168, v224
	v_add_f32_e32 v169, v169, v225
	v_lshlrev_b32_e32 v224, 16, v189
	v_and_b32_e32 v225, 0xffff0000, v189
	v_add_f32_e32 v222, v222, v224
	v_add_f32_e32 v223, v223, v225
	v_cvt_pk_bf16_f32 v214, v132, v133
	v_cvt_pk_bf16_f32 v215, v164, v165
	v_cvt_pk_bf16_f32 v216, v168, v169
	v_cvt_pk_bf16_f32 v217, v222, v223
	s_add_u32 s44, s48, 0x10100
	s_addc_u32 s45, s49, 0
	global_store_dwordx4 v226, v[214:217], s[44:45]
	global_load_dwordx4 v[156:159], v166, s[12:13]
	s_add_u32 s12, s12, 0x2000
	s_addc_u32 s13, s13, 0
	global_load_dwordx4 v[186:189], v166, s[20:21]
	s_add_u32 s20, s20, 0x2000
	s_addc_u32 s21, s21, 0
	s_waitcnt vmcnt(12)
; __device__ __forceinline__ unsigned cvt_pk_bf16(float lo, float hi) { const f32x2 v = {lo, hi}; const bf16x2_t b = __builtin_convertvector(v, bf16x2_t); return __builtin_bit_cast(unsigned, b); }
; __device__ __forceinline__ float bf_lo(unsigned u) { return __uint_as_float(u << 16); }
; __device__ __forceinline__ float bf_hi(unsigned u) { return __uint_as_float(u & 0xffff0000u); }
;     __device__ __forceinline__ void operator()(const f32x4 (&acc)[2][2][4][2], const Unit& u, int wr, int wc, int fr, int fq) const {
;     ...
;         for (int ai = 0; ai < 2; ++ai)
; #pragma unroll
;             for (int bj = 0; bj < 2; ++bj)
; #pragma unroll
;                 for (int m = 0; m < 4; ++m) {
;                     const u32x4 g = *((const u32x4*)Gs + ((size_t)(tile * 16 + (ai * 2 + bj) * 4 + m) * NTHREADS + tid));
;                     f32x4 y0 = acc[ai][bj][m][0], y1 = acc[ai][bj][m][1];
;                     y0[0] *= bf_lo(g.x); y0[1] *= bf_hi(g.x); y0[2] *= bf_lo(g.y); y0[3] *= bf_hi(g.y);
;                     y1[0] *= bf_lo(g.z); y1[1] *= bf_hi(g.z); y1[2] *= bf_lo(g.w); y1[3] *= bf_hi(g.w);
;                     u32x4* sp = (u32x4*)Sb + ((size_t)(tile * 16 + (ai * 2 + bj) * 4 + m) * NTHREADS + tid);
;                     if (br != 0) { const u32x4 t = *sp;
;                         y0[0] += bf_lo(t.x); y0[1] += bf_hi(t.x); y0[2] += bf_lo(t.y); y0[3] += bf_hi(t.y); y1[0] += bf_lo(t.z); y1[1] += bf_hi(t.z); y1[2] += bf_lo(t.w); y1[3] += bf_hi(t.w); }
;                     u32x4 w; w.x = cvt_pk_bf16(y0[0], y0[1]); w.y = cvt_pk_bf16(y0[2], y0[3]); w.z = cvt_pk_bf16(y1[0], y1[1]); w.w = cvt_pk_bf16(y1[2], y1[3]);
;                     if (br != 2) *sp = w;
;                     else {
;                         *(u32x4*)(MIXPRE + (size_t)(row0 + ai * 128 + m * 16) * DM + col00 + bj * 128) = w; }
	v_lshlrev_b32_e32 v224, 16, v160
	v_and_b32_e32 v225, 0xffff0000, v160
	v_mul_f32_e32 v132, v38, v224
	v_mul_f32_e32 v133, v39, v225
	v_lshlrev_b32_e32 v224, 16, v161
	v_and_b32_e32 v225, 0xffff0000, v161
	v_mul_f32_e32 v164, v40, v224
	v_mul_f32_e32 v165, v41, v225
	v_lshlrev_b32_e32 v224, 16, v162
	v_and_b32_e32 v225, 0xffff0000, v162
	v_mul_f32_e32 v168, v34, v224
	v_mul_f32_e32 v169, v35, v225
	v_lshlrev_b32_e32 v224, 16, v163
	v_and_b32_e32 v225, 0xffff0000, v163
	v_mul_f32_e32 v222, v36, v224
	v_mul_f32_e32 v223, v37, v225
	v_lshlrev_b32_e32 v224, 16, v202
	v_and_b32_e32 v225, 0xffff0000, v202
	v_add_f32_e32 v132, v132, v224
	v_add_f32_e32 v133, v133, v225
	v_lshlrev_b32_e32 v224, 16, v203
	v_and_b32_e32 v225, 0xffff0000, v203
	v_add_f32_e32 v164, v164, v224
	v_add_f32_e32 v165, v165, v225
	v_lshlrev_b32_e32 v224, 16, v204
	v_and_b32_e32 v225, 0xffff0000, v204
	v_add_f32_e32 v168, v168, v224
	v_add_f32_e32 v169, v169, v225
	v_lshlrev_b32_e32 v224, 16, v205
	v_and_b32_e32 v225, 0xffff0000, v205
	v_add_f32_e32 v222, v222, v224
	v_add_f32_e32 v223, v223, v225
	v_cvt_pk_bf16_f32 v218, v132, v133
	v_cvt_pk_bf16_f32 v219, v164, v165
	v_cvt_pk_bf16_f32 v220, v168, v169
	v_cvt_pk_bf16_f32 v221, v222, v223
	s_add_u32 s44, s48, 0x18100
	s_addc_u32 s45, s49, 0
	global_store_dwordx4 v226, v[218:221], s[44:45]
	global_load_dwordx4 v[160:163], v166, s[12:13]
	s_add_u32 s12, s12, 0x2000
	s_addc_u32 s13, s13, 0
	global_load_dwordx4 v[202:205], v166, s[20:21]
	s_add_u32 s20, s20, 0x2000
	s_addc_u32 s21, s21, 0
	s_waitcnt vmcnt(12)
	v_lshlrev_b32_e32 v224, 16, v174
	v_and_b32_e32 v225, 0xffff0000, v174
	v_mul_f32_e32 v132, v94, v224
	v_mul_f32_e32 v133, v95, v225
	v_lshlrev_b32_e32 v224, 16, v175
	v_and_b32_e32 v225, 0xffff0000, v175
	v_mul_f32_e32 v164, v96, v224
	v_mul_f32_e32 v165, v97, v225
	v_lshlrev_b32_e32 v224, 16, v176
	v_and_b32_e32 v225, 0xffff0000, v176
	v_mul_f32_e32 v168, v90, v224
	v_mul_f32_e32 v169, v91, v225
	v_lshlrev_b32_e32 v224, 16, v177
	v_and_b32_e32 v225, 0xffff0000, v177
	v_mul_f32_e32 v222, v92, v224
	v_mul_f32_e32 v223, v93, v225
	v_lshlrev_b32_e32 v224, 16, v206
	v_and_b32_e32 v225, 0xffff0000, v206
	v_add_f32_e32 v132, v132, v224
	v_add_f32_e32 v133, v133, v225
	v_lshlrev_b32_e32 v224, 16, v207
	v_and_b32_e32 v225, 0xffff0000, v207
	v_add_f32_e32 v164, v164, v224
	v_add_f32_e32 v165, v165, v225
	v_lshlrev_b32_e32 v224, 16, v208
	v_and_b32_e32 v225, 0xffff0000, v208
	v_add_f32_e32 v168, v168, v224
	v_add_f32_e32 v169, v169, v225
	v_lshlrev_b32_e32 v224, 16, v209
	v_and_b32_e32 v225, 0xffff0000, v209
	v_add_f32_e32 v222, v222, v224
	v_add_f32_e32 v223, v223, v225
	v_cvt_pk_bf16_f32 v214, v132, v133
	v_cvt_pk_bf16_f32 v215, v164, v165
	v_cvt_pk_bf16_f32 v216, v168, v169
	v_cvt_pk_bf16_f32 v217, v222, v223
	s_add_u32 s44, s48, 0x40000
	s_addc_u32 s45, s49, 0
	global_store_dwordx4 v226, v[214:217], s[44:45]
	global_load_dwordx4 v[174:177], v166, s[12:13]
	s_add_u32 s12, s12, 0x2000
	s_addc_u32 s13, s13, 0
	global_load_dwordx4 v[206:209], v166, s[20:21]
	s_add_u32 s20, s20, 0x2000
	s_addc_u32 s21, s21, 0
	s_waitcnt vmcnt(12)
	v_lshlrev_b32_e32 v224, 16, v178
	v_and_b32_e32 v225, 0xffff0000, v178
	v_mul_f32_e32 v132, v86, v224
	v_mul_f32_e32 v133, v87, v225
	v_lshlrev_b32_e32 v224, 16, v179
	v_and_b32_e32 v225, 0xffff0000, v179
	v_mul_f32_e32 v164, v88, v224
	v_mul_f32_e32 v165, v89, v225
	v_lshlrev_b32_e32 v224, 16, v180
	v_and_b32_e32 v225, 0xffff0000, v180
	v_mul_f32_e32 v168, v82, v224
	v_mul_f32_e32 v169, v83, v225
	v_lshlrev_b32_e32 v224, 16, v181
	v_and_b32_e32 v225, 0xffff0000, v181
	v_mul_f32_e32 v222, v84, v224
	v_mul_f32_e32 v223, v85, v225
	v_lshlrev_b32_e32 v224, 16, v210
	v_and_b32_e32 v225, 0xffff0000, v210
	v_add_f32_e32 v132, v132, v224
	v_add_f32_e32 v133, v133, v225
	v_lshlrev_b32_e32 v224, 16, v211
	v_and_b32_e32 v225, 0xffff0000, v211
	v_add_f32_e32 v164, v164, v224
	v_add_f32_e32 v165, v165, v225
	v_lshlrev_b32_e32 v224, 16, v212
	v_and_b32_e32 v225, 0xffff0000, v212
	v_add_f32_e32 v168, v168, v224
	v_add_f32_e32 v169, v169, v225
	v_lshlrev_b32_e32 v224, 16, v213
	v_and_b32_e32 v225, 0xffff0000, v213
	v_add_f32_e32 v222, v222, v224
	v_add_f32_e32 v223, v223, v225
	v_cvt_pk_bf16_f32 v218, v132, v133
	v_cvt_pk_bf16_f32 v219, v164, v165
	v_cvt_pk_bf16_f32 v220, v168, v169
	v_cvt_pk_bf16_f32 v221, v222, v223
	s_add_u32 s44, s48, 0x48000
	s_addc_u32 s45, s49, 0
	global_store_dwordx4 v226, v[218:221], s[44:45]
	global_load_dwordx4 v[178:181], v166, s[12:13]
	s_add_u32 s12, s12, 0x2000
	s_addc_u32 s13, s13, 0
	global_load_dwordx4 v[210:213], v166, s[20:21]
	s_add_u32 s20, s20, 0x2000
	s_addc_u32 s21, s21, 0
	s_waitcnt vmcnt(12)
	v_lshlrev_b32_e32 v224, 16, v152
	v_and_b32_e32 v225, 0xffff0000, v152
	v_mul_f32_e32 v132, v78, v224
	v_mul_f32_e32 v133, v79, v225
	v_lshlrev_b32_e32 v224, 16, v153
	v_and_b32_e32 v225, 0xffff0000, v153
	v_mul_f32_e32 v164, v80, v224
	v_mul_f32_e32 v165, v81, v225
	v_lshlrev_b32_e32 v224, 16, v154
	v_and_b32_e32 v225, 0xffff0000, v154
	v_mul_f32_e32 v168, v74, v224
	v_mul_f32_e32 v169, v75, v225
	v_lshlrev_b32_e32 v224, 16, v155
	v_and_b32_e32 v225, 0xffff0000, v155
	v_mul_f32_e32 v222, v76, v224
	v_mul_f32_e32 v223, v77, v225
	v_lshlrev_b32_e32 v224, 16, v182
	v_and_b32_e32 v225, 0xffff0000, v182
	v_add_f32_e32 v132, v132, v224
	v_add_f32_e32 v133, v133, v225
	v_lshlrev_b32_e32 v224, 16, v183
	v_and_b32_e32 v225, 0xffff0000, v183
	v_add_f32_e32 v164, v164, v224
	v_add_f32_e32 v165, v165, v225
	v_lshlrev_b32_e32 v224, 16, v184
	v_and_b32_e32 v225, 0xffff0000, v184
	v_add_f32_e32 v168, v168, v224
	v_add_f32_e32 v169, v169, v225
	v_lshlrev_b32_e32 v224, 16, v185
	v_and_b32_e32 v225, 0xffff0000, v185
	v_add_f32_e32 v222, v222, v224
	v_add_f32_e32 v223, v223, v225
	v_cvt_pk_bf16_f32 v214, v132, v133
	v_cvt_pk_bf16_f32 v215, v164, v165
	v_cvt_pk_bf16_f32 v216, v168, v169
	v_cvt_pk_bf16_f32 v217, v222, v223
	s_add_u32 s44, s48, 0x50000
	s_addc_u32 s45, s49, 0
	global_store_dwordx4 v226, v[214:217], s[44:45]
	global_load_dwordx4 v[152:155], v166, s[12:13]
	s_add_u32 s12, s12, 0x2000
	s_addc_u32 s13, s13, 0
	global_load_dwordx4 v[182:185], v166, s[20:21]
	s_add_u32 s20, s20, 0x2000
	s_addc_u32 s21, s21, 0
	s_waitcnt vmcnt(12)
; __device__ __forceinline__ unsigned cvt_pk_bf16(float lo, float hi) { const f32x2 v = {lo, hi}; const bf16x2_t b = __builtin_convertvector(v, bf16x2_t); return __builtin_bit_cast(unsigned, b); }
; __device__ __forceinline__ float bf_lo(unsigned u) { return __uint_as_float(u << 16); }
; __device__ __forceinline__ float bf_hi(unsigned u) { return __uint_as_float(u & 0xffff0000u); }
;     __device__ __forceinline__ void operator()(const f32x4 (&acc)[2][2][4][2], const Unit& u, int wr, int wc, int fr, int fq) const {
;     ...
;         for (int ai = 0; ai < 2; ++ai)
; #pragma unroll
;             for (int bj = 0; bj < 2; ++bj)
; #pragma unroll
;                 for (int m = 0; m < 4; ++m) {
;                     const u32x4 g = *((const u32x4*)Gs + ((size_t)(tile * 16 + (ai * 2 + bj) * 4 + m) * NTHREADS + tid));
;                     f32x4 y0 = acc[ai][bj][m][0], y1 = acc[ai][bj][m][1];
;                     y0[0] *= bf_lo(g.x); y0[1] *= bf_hi(g.x); y0[2] *= bf_lo(g.y); y0[3] *= bf_hi(g.y);
;                     y1[0] *= bf_lo(g.z); y1[1] *= bf_hi(g.z); y1[2] *= bf_lo(g.w); y1[3] *= bf_hi(g.w);
;                     u32x4* sp = (u32x4*)Sb + ((size_t)(tile * 16 + (ai * 2 + bj) * 4 + m) * NTHREADS + tid);
;                     if (br != 0) { const u32x4 t = *sp;
;                         y0[0] += bf_lo(t.x); y0[1] += bf_hi(t.x); y0[2] += bf_lo(t.y); y0[3] += bf_hi(t.y); y1[0] += bf_lo(t.z); y1[1] += bf_hi(t.z); y1[2] += bf_lo(t.w); y1[3] += bf_hi(t.w); }
;                     u32x4 w; w.x = cvt_pk_bf16(y0[0], y0[1]); w.y = cvt_pk_bf16(y0[2], y0[3]); w.z = cvt_pk_bf16(y1[0], y1[1]); w.w = cvt_pk_bf16(y1[2], y1[3]);
;                     if (br != 2) *sp = w;
;                     else {
;                         *(u32x4*)(MIXPRE + (size_t)(row0 + ai * 128 + m * 16) * DM + col00 + bj * 128) = w; }
	v_lshlrev_b32_e32 v224, 16, v156
	v_and_b32_e32 v225, 0xffff0000, v156
	v_mul_f32_e32 v132, v70, v224
	v_mul_f32_e32 v133, v71, v225
	v_lshlrev_b32_e32 v224, 16, v157
	v_and_b32_e32 v225, 0xffff0000, v157
	v_mul_f32_e32 v164, v72, v224
	v_mul_f32_e32 v165, v73, v225
	v_lshlrev_b32_e32 v224, 16, v158
	v_and_b32_e32 v225, 0xffff0000, v158
	v_mul_f32_e32 v168, v66, v224
	v_mul_f32_e32 v169, v67, v225
	v_lshlrev_b32_e32 v224, 16, v159
	v_and_b32_e32 v225, 0xffff0000, v159
	v_mul_f32_e32 v222, v68, v224
	v_mul_f32_e32 v223, v69, v225
	v_lshlrev_b32_e32 v224, 16, v186
	v_and_b32_e32 v225, 0xffff0000, v186
	v_add_f32_e32 v132, v132, v224
	v_add_f32_e32 v133, v133, v225
	v_lshlrev_b32_e32 v224, 16, v187
	v_and_b32_e32 v225, 0xffff0000, v187
	v_add_f32_e32 v164, v164, v224
	v_add_f32_e32 v165, v165, v225
	v_lshlrev_b32_e32 v224, 16, v188
	v_and_b32_e32 v225, 0xffff0000, v188
	v_add_f32_e32 v168, v168, v224
	v_add_f32_e32 v169, v169, v225
	v_lshlrev_b32_e32 v224, 16, v189
	v_and_b32_e32 v225, 0xffff0000, v189
	v_add_f32_e32 v222, v222, v224
	v_add_f32_e32 v223, v223, v225
	v_cvt_pk_bf16_f32 v218, v132, v133
	v_cvt_pk_bf16_f32 v219, v164, v165
	v_cvt_pk_bf16_f32 v220, v168, v169
	v_cvt_pk_bf16_f32 v221, v222, v223
	s_add_u32 s44, s48, 0x58000
	s_addc_u32 s45, s49, 0
	global_store_dwordx4 v226, v[218:221], s[44:45]
	s_waitcnt vmcnt(10)
	v_lshlrev_b32_e32 v224, 16, v160
	v_and_b32_e32 v225, 0xffff0000, v160
	v_mul_f32_e32 v132, v30, v224
	v_mul_f32_e32 v133, v31, v225
	v_lshlrev_b32_e32 v224, 16, v161
	v_and_b32_e32 v225, 0xffff0000, v161
	v_mul_f32_e32 v164, v32, v224
	v_mul_f32_e32 v165, v33, v225
	v_lshlrev_b32_e32 v224, 16, v162
	v_and_b32_e32 v225, 0xffff0000, v162
	v_mul_f32_e32 v168, v26, v224
	v_mul_f32_e32 v169, v27, v225
	v_lshlrev_b32_e32 v224, 16, v163
	v_and_b32_e32 v225, 0xffff0000, v163
	v_mul_f32_e32 v222, v28, v224
	v_mul_f32_e32 v223, v29, v225
	v_lshlrev_b32_e32 v224, 16, v202
	v_and_b32_e32 v225, 0xffff0000, v202
	v_add_f32_e32 v132, v132, v224
	v_add_f32_e32 v133, v133, v225
	v_lshlrev_b32_e32 v224, 16, v203
	v_and_b32_e32 v225, 0xffff0000, v203
	v_add_f32_e32 v164, v164, v224
	v_add_f32_e32 v165, v165, v225
	v_lshlrev_b32_e32 v224, 16, v204
	v_and_b32_e32 v225, 0xffff0000, v204
	v_add_f32_e32 v168, v168, v224
	v_add_f32_e32 v169, v169, v225
	v_lshlrev_b32_e32 v224, 16, v205
	v_and_b32_e32 v225, 0xffff0000, v205
	v_add_f32_e32 v222, v222, v224
	v_add_f32_e32 v223, v223, v225
	v_cvt_pk_bf16_f32 v214, v132, v133
	v_cvt_pk_bf16_f32 v215, v164, v165
	v_cvt_pk_bf16_f32 v216, v168, v169
	v_cvt_pk_bf16_f32 v217, v222, v223
	s_add_u32 s44, s48, 0x40100
	s_addc_u32 s45, s49, 0
	global_store_dwordx4 v226, v[214:217], s[44:45]
	s_waitcnt vmcnt(8)
	v_lshlrev_b32_e32 v224, 16, v174
	v_and_b32_e32 v225, 0xffff0000, v174
	v_mul_f32_e32 v132, v22, v224
	v_mul_f32_e32 v133, v23, v225
	v_lshlrev_b32_e32 v224, 16, v175
	v_and_b32_e32 v225, 0xffff0000, v175
	v_mul_f32_e32 v164, v24, v224
	v_mul_f32_e32 v165, v25, v225
	v_lshlrev_b32_e32 v224, 16, v176
	v_and_b32_e32 v225, 0xffff0000, v176
	v_mul_f32_e32 v168, v18, v224
	v_mul_f32_e32 v169, v19, v225
	v_lshlrev_b32_e32 v224, 16, v177
	v_and_b32_e32 v225, 0xffff0000, v177
	v_mul_f32_e32 v222, v20, v224
	v_mul_f32_e32 v223, v21, v225
	v_lshlrev_b32_e32 v224, 16, v206
	v_and_b32_e32 v225, 0xffff0000, v206
	v_add_f32_e32 v132, v132, v224
	v_add_f32_e32 v133, v133, v225
	v_lshlrev_b32_e32 v224, 16, v207
	v_and_b32_e32 v225, 0xffff0000, v207
	v_add_f32_e32 v164, v164, v224
	v_add_f32_e32 v165, v165, v225
	v_lshlrev_b32_e32 v224, 16, v208
	v_and_b32_e32 v225, 0xffff0000, v208
	v_add_f32_e32 v168, v168, v224
	v_add_f32_e32 v169, v169, v225
	v_lshlrev_b32_e32 v224, 16, v209
	v_and_b32_e32 v225, 0xffff0000, v209
	v_add_f32_e32 v222, v222, v224
	v_add_f32_e32 v223, v223, v225
	v_cvt_pk_bf16_f32 v218, v132, v133
	v_cvt_pk_bf16_f32 v219, v164, v165
	v_cvt_pk_bf16_f32 v220, v168, v169
	v_cvt_pk_bf16_f32 v221, v222, v223
	s_add_u32 s44, s48, 0x48100
	s_addc_u32 s45, s49, 0
	global_store_dwordx4 v226, v[218:221], s[44:45]
	s_waitcnt vmcnt(6)
	v_lshlrev_b32_e32 v224, 16, v178
	v_and_b32_e32 v225, 0xffff0000, v178
	v_mul_f32_e32 v132, v14, v224
	v_mul_f32_e32 v133, v15, v225
	v_lshlrev_b32_e32 v224, 16, v179
	v_and_b32_e32 v225, 0xffff0000, v179
	v_mul_f32_e32 v164, v16, v224
	v_mul_f32_e32 v165, v17, v225
	v_lshlrev_b32_e32 v224, 16, v180
	v_and_b32_e32 v225, 0xffff0000, v180
	v_mul_f32_e32 v168, v10, v224
	v_mul_f32_e32 v169, v11, v225
	v_lshlrev_b32_e32 v224, 16, v181
	v_and_b32_e32 v225, 0xffff0000, v181
	v_mul_f32_e32 v222, v12, v224
	v_mul_f32_e32 v223, v13, v225
	v_lshlrev_b32_e32 v224, 16, v210
	v_and_b32_e32 v225, 0xffff0000, v210
	v_add_f32_e32 v132, v132, v224
	v_add_f32_e32 v133, v133, v225
	v_lshlrev_b32_e32 v224, 16, v211
	v_and_b32_e32 v225, 0xffff0000, v211
	v_add_f32_e32 v164, v164, v224
	v_add_f32_e32 v165, v165, v225
	v_lshlrev_b32_e32 v224, 16, v212
	v_and_b32_e32 v225, 0xffff0000, v212
	v_add_f32_e32 v168, v168, v224
	v_add_f32_e32 v169, v169, v225
	v_lshlrev_b32_e32 v224, 16, v213
	v_and_b32_e32 v225, 0xffff0000, v213
	v_add_f32_e32 v222, v222, v224
	v_add_f32_e32 v223, v223, v225
	v_cvt_pk_bf16_f32 v214, v132, v133
	v_cvt_pk_bf16_f32 v215, v164, v165
	v_cvt_pk_bf16_f32 v216, v168, v169
	v_cvt_pk_bf16_f32 v217, v222, v223
	s_add_u32 s44, s48, 0x50100
	s_addc_u32 s45, s49, 0
	global_store_dwordx4 v226, v[214:217], s[44:45]
	s_waitcnt vmcnt(4)
	v_lshlrev_b32_e32 v224, 16, v152
	v_and_b32_e32 v225, 0xffff0000, v152
	v_mul_f32_e32 v132, v6, v224
	v_mul_f32_e32 v133, v7, v225
	v_lshlrev_b32_e32 v224, 16, v153
	v_and_b32_e32 v225, 0xffff0000, v153
	v_mul_f32_e32 v164, v8, v224
	v_mul_f32_e32 v165, v9, v225
	v_lshlrev_b32_e32 v224, 16, v154
	v_and_b32_e32 v225, 0xffff0000, v154
	v_mul_f32_e32 v168, v2, v224
	v_mul_f32_e32 v169, v3, v225
	v_lshlrev_b32_e32 v224, 16, v155
	v_and_b32_e32 v225, 0xffff0000, v155
	v_mul_f32_e32 v222, v4, v224
	v_mul_f32_e32 v223, v5, v225
	v_lshlrev_b32_e32 v224, 16, v182
	v_and_b32_e32 v225, 0xffff0000, v182
	v_add_f32_e32 v132, v132, v224
	v_add_f32_e32 v133, v133, v225
	v_lshlrev_b32_e32 v224, 16, v183
	v_and_b32_e32 v225, 0xffff0000, v183
	v_add_f32_e32 v164, v164, v224
	v_add_f32_e32 v165, v165, v225
	v_lshlrev_b32_e32 v224, 16, v184
	v_and_b32_e32 v225, 0xffff0000, v184
	v_add_f32_e32 v168, v168, v224
	v_add_f32_e32 v169, v169, v225
	v_lshlrev_b32_e32 v224, 16, v185
	v_and_b32_e32 v225, 0xffff0000, v185
	v_add_f32_e32 v222, v222, v224
	v_add_f32_e32 v223, v223, v225
	v_cvt_pk_bf16_f32 v218, v132, v133
	v_cvt_pk_bf16_f32 v219, v164, v165
	v_cvt_pk_bf16_f32 v220, v168, v169
	v_cvt_pk_bf16_f32 v221, v222, v223
	s_add_u32 s44, s48, 0x58100
	s_addc_u32 s45, s49, 0
	global_store_dwordx4 v226, v[218:221], s[44:45]
	s_branch .LBB0_304
; __device__ __forceinline__ unsigned cvt_pk_bf16(float lo, float hi) { const f32x2 v = {lo, hi}; const bf16x2_t b = __builtin_convertvector(v, bf16x2_t); return __builtin_bit_cast(unsigned, b); }
; __device__ __forceinline__ float bf_lo(unsigned u) { return __uint_as_float(u << 16); }
; __device__ __forceinline__ float bf_hi(unsigned u) { return __uint_as_float(u & 0xffff0000u); }
;     __device__ __forceinline__ void operator()(const f32x4 (&acc)[2][2][4][2], const Unit& u, int wr, int wc, int fr, int fq) const {
;     ...
; #pragma unroll
;         for (int ai = 0; ai < 2; ++ai)
; #pragma unroll
;             for (int bj = 0; bj < 2; ++bj)
; #pragma unroll
;                 for (int m = 0; m < 4; ++m) {
;                     const u32x4 g = *((const u32x4*)Gs + ((size_t)(tile * 16 + (ai * 2 + bj) * 4 + m) * NTHREADS + tid));
;                     f32x4 y0 = acc[ai][bj][m][0], y1 = acc[ai][bj][m][1];
;                     y0[0] *= bf_lo(g.x); y0[1] *= bf_hi(g.x); y0[2] *= bf_lo(g.y); y0[3] *= bf_hi(g.y);
;                     y1[0] *= bf_lo(g.z); y1[1] *= bf_hi(g.z); y1[2] *= bf_lo(g.w); y1[3] *= bf_hi(g.w);
;                     u32x4* sp = (u32x4*)Sb + ((size_t)(tile * 16 + (ai * 2 + bj) * 4 + m) * NTHREADS + tid);
;                     if (br != 0) { const u32x4 t = *sp;
;                         y0[0] += bf_lo(t.x); y0[1] += bf_hi(t.x); y0[2] += bf_lo(t.y); y0[3] += bf_hi(t.y); y1[0] += bf_lo(t.z); y1[1] += bf_hi(t.z); y1[2] += bf_lo(t.w); y1[3] += bf_hi(t.w); }
;                     u32x4 w; w.x = cvt_pk_bf16(y0[0], y0[1]); w.y = cvt_pk_bf16(y0[2], y0[3]); w.z = cvt_pk_bf16(y1[0], y1[1]); w.w = cvt_pk_bf16(y1[2], y1[3]);
;                     if (br != 2) *sp = w;
;                     else {
;                         *(u32x4*)(MIXPRE + (size_t)(row0 + ai * 128 + m * 16) * DM + col00 + bj * 128) = w; }
;                 }
.Lpl_br1:
	s_add_u32 s12, s12, 0x2000
	s_addc_u32 s13, s13, 0
	global_load_dwordx4 v[182:185], v166, s[20:21]
	s_add_u32 s20, s20, 0x2000
	s_addc_u32 s21, s21, 0
	s_add_u32 s12, s12, 0x2000
	s_addc_u32 s13, s13, 0
	global_load_dwordx4 v[186:189], v166, s[20:21]
	s_add_u32 s20, s20, 0x2000
	s_addc_u32 s21, s21, 0
	s_add_u32 s12, s12, 0x2000
	s_addc_u32 s13, s13, 0
	global_load_dwordx4 v[202:205], v166, s[20:21]
	s_add_u32 s20, s20, 0x2000
	s_addc_u32 s21, s21, 0
	s_add_u32 s12, s12, 0x2000
	s_addc_u32 s13, s13, 0
	global_load_dwordx4 v[206:209], v166, s[20:21]
	s_add_u32 s20, s20, 0x2000
	s_addc_u32 s21, s21, 0
	s_add_u32 s12, s12, 0x2000
	s_addc_u32 s13, s13, 0
	global_load_dwordx4 v[210:213], v166, s[20:21]
	s_add_u32 s20, s20, 0x2000
	s_addc_u32 s21, s21, 0
	s_waitcnt vmcnt(4)
	v_lshlrev_b32_e32 v224, 16, v230
	v_and_b32_e32 v225, 0xffff0000, v230
	v_mul_f32_e32 v132, v126, v224
	v_mul_f32_e32 v133, v127, v225
	v_lshlrev_b32_e32 v224, 16, v231
	v_and_b32_e32 v225, 0xffff0000, v231
	v_mul_f32_e32 v164, v128, v224
	v_mul_f32_e32 v165, v129, v225
	v_lshlrev_b32_e32 v224, 16, v232
	v_and_b32_e32 v225, 0xffff0000, v232
	v_mul_f32_e32 v168, v122, v224
	v_mul_f32_e32 v169, v123, v225
	v_lshlrev_b32_e32 v224, 16, v233
	v_and_b32_e32 v225, 0xffff0000, v233
	v_mul_f32_e32 v222, v124, v224
	v_mul_f32_e32 v223, v125, v225
	v_lshlrev_b32_e32 v224, 16, v182
	v_and_b32_e32 v225, 0xffff0000, v182
	v_add_f32_e32 v132, v132, v224
	v_add_f32_e32 v133, v133, v225
	v_lshlrev_b32_e32 v224, 16, v183
	v_and_b32_e32 v225, 0xffff0000, v183
	v_add_f32_e32 v164, v164, v224
	v_add_f32_e32 v165, v165, v225
	v_lshlrev_b32_e32 v224, 16, v184
	v_and_b32_e32 v225, 0xffff0000, v184
	v_add_f32_e32 v168, v168, v224
	v_add_f32_e32 v169, v169, v225
	v_lshlrev_b32_e32 v224, 16, v185
	v_and_b32_e32 v225, 0xffff0000, v185
	v_add_f32_e32 v222, v222, v224
	v_add_f32_e32 v223, v223, v225
	v_cvt_pk_bf16_f32 v214, v132, v133
	v_cvt_pk_bf16_f32 v215, v164, v165
	v_cvt_pk_bf16_f32 v216, v168, v169
	v_cvt_pk_bf16_f32 v217, v222, v223
	global_store_dwordx4 v166, v[214:217], s[44:45]
	s_add_u32 s44, s44, 0x2000
	s_addc_u32 s45, s45, 0
	s_add_u32 s12, s12, 0x2000
	s_addc_u32 s13, s13, 0
	global_load_dwordx4 v[182:185], v166, s[20:21]
	s_add_u32 s20, s20, 0x2000
	s_addc_u32 s21, s21, 0
	s_waitcnt vmcnt(5)
	v_lshlrev_b32_e32 v224, 16, v234
	v_and_b32_e32 v225, 0xffff0000, v234
	v_mul_f32_e32 v132, v118, v224
	v_mul_f32_e32 v133, v119, v225
	v_lshlrev_b32_e32 v224, 16, v235
	v_and_b32_e32 v225, 0xffff0000, v235
	v_mul_f32_e32 v164, v120, v224
	v_mul_f32_e32 v165, v121, v225
	v_lshlrev_b32_e32 v224, 16, v236
	v_and_b32_e32 v225, 0xffff0000, v236
	v_mul_f32_e32 v168, v114, v224
	v_mul_f32_e32 v169, v115, v225
	v_lshlrev_b32_e32 v224, 16, v237
	v_and_b32_e32 v225, 0xffff0000, v237
	v_mul_f32_e32 v222, v116, v224
	v_mul_f32_e32 v223, v117, v225
	v_lshlrev_b32_e32 v224, 16, v186
	v_and_b32_e32 v225, 0xffff0000, v186
	v_add_f32_e32 v132, v132, v224
	v_add_f32_e32 v133, v133, v225
	v_lshlrev_b32_e32 v224, 16, v187
	v_and_b32_e32 v225, 0xffff0000, v187
	v_add_f32_e32 v164, v164, v224
	v_add_f32_e32 v165, v165, v225
	v_lshlrev_b32_e32 v224, 16, v188
	v_and_b32_e32 v225, 0xffff0000, v188
	v_add_f32_e32 v168, v168, v224
	v_add_f32_e32 v169, v169, v225
	v_lshlrev_b32_e32 v224, 16, v189
	v_and_b32_e32 v225, 0xffff0000, v189
	v_add_f32_e32 v222, v222, v224
	v_add_f32_e32 v223, v223, v225
	v_cvt_pk_bf16_f32 v218, v132, v133
	v_cvt_pk_bf16_f32 v219, v164, v165
	v_cvt_pk_bf16_f32 v220, v168, v169
	v_cvt_pk_bf16_f32 v221, v222, v223
	global_store_dwordx4 v166, v[218:221], s[44:45]
	s_add_u32 s44, s44, 0x2000
	s_addc_u32 s45, s45, 0
	global_load_dwordx4 v[156:159], v166, s[12:13]
	s_add_u32 s12, s12, 0x2000
	s_addc_u32 s13, s13, 0
	global_load_dwordx4 v[186:189], v166, s[20:21]
	s_add_u32 s20, s20, 0x2000
	s_addc_u32 s21, s21, 0
	s_waitcnt vmcnt(7)
	v_lshlrev_b32_e32 v224, 16, v238
	v_and_b32_e32 v225, 0xffff0000, v238
	v_mul_f32_e32 v132, v110, v224
	v_mul_f32_e32 v133, v111, v225
	v_lshlrev_b32_e32 v224, 16, v239
	v_and_b32_e32 v225, 0xffff0000, v239
	v_mul_f32_e32 v164, v112, v224
	v_mul_f32_e32 v165, v113, v225
	v_lshlrev_b32_e32 v224, 16, v240
	v_and_b32_e32 v225, 0xffff0000, v240
	v_mul_f32_e32 v168, v106, v224
	v_mul_f32_e32 v169, v107, v225
	v_lshlrev_b32_e32 v224, 16, v241
	v_and_b32_e32 v225, 0xffff0000, v241
	v_mul_f32_e32 v222, v108, v224
	v_mul_f32_e32 v223, v109, v225
	v_lshlrev_b32_e32 v224, 16, v202
	v_and_b32_e32 v225, 0xffff0000, v202
	v_add_f32_e32 v132, v132, v224
	v_add_f32_e32 v133, v133, v225
	v_lshlrev_b32_e32 v224, 16, v203
	v_and_b32_e32 v225, 0xffff0000, v203
	v_add_f32_e32 v164, v164, v224
	v_add_f32_e32 v165, v165, v225
	v_lshlrev_b32_e32 v224, 16, v204
	v_and_b32_e32 v225, 0xffff0000, v204
	v_add_f32_e32 v168, v168, v224
	v_add_f32_e32 v169, v169, v225
	v_lshlrev_b32_e32 v224, 16, v205
	v_and_b32_e32 v225, 0xffff0000, v205
	v_add_f32_e32 v222, v222, v224
	v_add_f32_e32 v223, v223, v225
	v_cvt_pk_bf16_f32 v214, v132, v133
	v_cvt_pk_bf16_f32 v215, v164, v165
	v_cvt_pk_bf16_f32 v216, v168, v169
	v_cvt_pk_bf16_f32 v217, v222, v223
	global_store_dwordx4 v166, v[214:217], s[44:45]
	s_add_u32 s44, s44, 0x2000
	s_addc_u32 s45, s45, 0
	global_load_dwordx4 v[160:163], v166, s[12:13]
	s_add_u32 s12, s12, 0x2000
	s_addc_u32 s13, s13, 0
	global_load_dwordx4 v[202:205], v166, s[20:21]
	s_add_u32 s20, s20, 0x2000
	s_addc_u32 s21, s21, 0
	s_waitcnt vmcnt(9)
; __device__ __forceinline__ unsigned cvt_pk_bf16(float lo, float hi) { const f32x2 v = {lo, hi}; const bf16x2_t b = __builtin_convertvector(v, bf16x2_t); return __builtin_bit_cast(unsigned, b); }
; __device__ __forceinline__ float bf_lo(unsigned u) { return __uint_as_float(u << 16); }
; __device__ __forceinline__ float bf_hi(unsigned u) { return __uint_as_float(u & 0xffff0000u); }
;     __device__ __forceinline__ void operator()(const f32x4 (&acc)[2][2][4][2], const Unit& u, int wr, int wc, int fr, int fq) const {
;     ...
; #pragma unroll
;         for (int ai = 0; ai < 2; ++ai)
; #pragma unroll
;             for (int bj = 0; bj < 2; ++bj)
; #pragma unroll
;                 for (int m = 0; m < 4; ++m) {
;                     const u32x4 g = *((const u32x4*)Gs + ((size_t)(tile * 16 + (ai * 2 + bj) * 4 + m) * NTHREADS + tid));
;                     f32x4 y0 = acc[ai][bj][m][0], y1 = acc[ai][bj][m][1];
;                     y0[0] *= bf_lo(g.x); y0[1] *= bf_hi(g.x); y0[2] *= bf_lo(g.y); y0[3] *= bf_hi(g.y);
;                     y1[0] *= bf_lo(g.z); y1[1] *= bf_hi(g.z); y1[2] *= bf_lo(g.w); y1[3] *= bf_hi(g.w);
;                     u32x4* sp = (u32x4*)Sb + ((size_t)(tile * 16 + (ai * 2 + bj) * 4 + m) * NTHREADS + tid);
;                     if (br != 0) { const u32x4 t = *sp;
;                         y0[0] += bf_lo(t.x); y0[1] += bf_hi(t.x); y0[2] += bf_lo(t.y); y0[3] += bf_hi(t.y); y1[0] += bf_lo(t.z); y1[1] += bf_hi(t.z); y1[2] += bf_lo(t.w); y1[3] += bf_hi(t.w); }
;                     u32x4 w; w.x = cvt_pk_bf16(y0[0], y0[1]); w.y = cvt_pk_bf16(y0[2], y0[3]); w.z = cvt_pk_bf16(y1[0], y1[1]); w.w = cvt_pk_bf16(y1[2], y1[3]);
;                     if (br != 2) *sp = w;
;                     else {
;                         *(u32x4*)(MIXPRE + (size_t)(row0 + ai * 128 + m * 16) * DM + col00 + bj * 128) = w; }
;                 }
	v_lshlrev_b32_e32 v224, 16, v242
	v_and_b32_e32 v225, 0xffff0000, v242
	v_mul_f32_e32 v132, v102, v224
	v_mul_f32_e32 v133, v103, v225
	v_lshlrev_b32_e32 v224, 16, v243
	v_and_b32_e32 v225, 0xffff0000, v243
	v_mul_f32_e32 v164, v104, v224
	v_mul_f32_e32 v165, v105, v225
	v_lshlrev_b32_e32 v224, 16, v244
	v_and_b32_e32 v225, 0xffff0000, v244
	v_mul_f32_e32 v168, v98, v224
	v_mul_f32_e32 v169, v99, v225
	v_lshlrev_b32_e32 v224, 16, v245
	v_and_b32_e32 v225, 0xffff0000, v245
	v_mul_f32_e32 v222, v100, v224
	v_mul_f32_e32 v223, v101, v225
	v_lshlrev_b32_e32 v224, 16, v206
	v_and_b32_e32 v225, 0xffff0000, v206
	v_add_f32_e32 v132, v132, v224
	v_add_f32_e32 v133, v133, v225
	v_lshlrev_b32_e32 v224, 16, v207
	v_and_b32_e32 v225, 0xffff0000, v207
	v_add_f32_e32 v164, v164, v224
	v_add_f32_e32 v165, v165, v225
	v_lshlrev_b32_e32 v224, 16, v208
	v_and_b32_e32 v225, 0xffff0000, v208
	v_add_f32_e32 v168, v168, v224
	v_add_f32_e32 v169, v169, v225
	v_lshlrev_b32_e32 v224, 16, v209
	v_and_b32_e32 v225, 0xffff0000, v209
	v_add_f32_e32 v222, v222, v224
	v_add_f32_e32 v223, v223, v225
	v_cvt_pk_bf16_f32 v218, v132, v133
	v_cvt_pk_bf16_f32 v219, v164, v165
	v_cvt_pk_bf16_f32 v220, v168, v169
	v_cvt_pk_bf16_f32 v221, v222, v223
	global_store_dwordx4 v166, v[218:221], s[44:45]
	s_add_u32 s44, s44, 0x2000
	s_addc_u32 s45, s45, 0
	global_load_dwordx4 v[174:177], v166, s[12:13]
	s_add_u32 s12, s12, 0x2000
	s_addc_u32 s13, s13, 0
	global_load_dwordx4 v[206:209], v166, s[20:21]
	s_add_u32 s20, s20, 0x2000
	s_addc_u32 s21, s21, 0
	s_waitcnt vmcnt(11)
	v_lshlrev_b32_e32 v224, 16, v246
	v_and_b32_e32 v225, 0xffff0000, v246
	v_mul_f32_e32 v132, v62, v224
	v_mul_f32_e32 v133, v63, v225
	v_lshlrev_b32_e32 v224, 16, v247
	v_and_b32_e32 v225, 0xffff0000, v247
	v_mul_f32_e32 v164, v64, v224
	v_mul_f32_e32 v165, v65, v225
	v_lshlrev_b32_e32 v224, 16, v248
	v_and_b32_e32 v225, 0xffff0000, v248
	v_mul_f32_e32 v168, v58, v224
	v_mul_f32_e32 v169, v59, v225
	v_lshlrev_b32_e32 v224, 16, v249
	v_and_b32_e32 v225, 0xffff0000, v249
	v_mul_f32_e32 v222, v60, v224
	v_mul_f32_e32 v223, v61, v225
	v_lshlrev_b32_e32 v224, 16, v210
	v_and_b32_e32 v225, 0xffff0000, v210
	v_add_f32_e32 v132, v132, v224
	v_add_f32_e32 v133, v133, v225
	v_lshlrev_b32_e32 v224, 16, v211
	v_and_b32_e32 v225, 0xffff0000, v211
	v_add_f32_e32 v164, v164, v224
	v_add_f32_e32 v165, v165, v225
	v_lshlrev_b32_e32 v224, 16, v212
	v_and_b32_e32 v225, 0xffff0000, v212
	v_add_f32_e32 v168, v168, v224
	v_add_f32_e32 v169, v169, v225
	v_lshlrev_b32_e32 v224, 16, v213
	v_and_b32_e32 v225, 0xffff0000, v213
	v_add_f32_e32 v222, v222, v224
	v_add_f32_e32 v223, v223, v225
	v_cvt_pk_bf16_f32 v214, v132, v133
	v_cvt_pk_bf16_f32 v215, v164, v165
	v_cvt_pk_bf16_f32 v216, v168, v169
	v_cvt_pk_bf16_f32 v217, v222, v223
	global_store_dwordx4 v166, v[214:217], s[44:45]
	s_add_u32 s44, s44, 0x2000
	s_addc_u32 s45, s45, 0
	global_load_dwordx4 v[178:181], v166, s[12:13]
	s_add_u32 s12, s12, 0x2000
	s_addc_u32 s13, s13, 0
	global_load_dwordx4 v[210:213], v166, s[20:21]
	s_add_u32 s20, s20, 0x2000
	s_addc_u32 s21, s21, 0
	s_waitcnt vmcnt(12)
	v_lshlrev_b32_e32 v224, 16, v198
	v_and_b32_e32 v225, 0xffff0000, v198
	v_mul_f32_e32 v132, v54, v224
	v_mul_f32_e32 v133, v55, v225
	v_lshlrev_b32_e32 v224, 16, v199
	v_and_b32_e32 v225, 0xffff0000, v199
	v_mul_f32_e32 v164, v56, v224
	v_mul_f32_e32 v165, v57, v225
	v_lshlrev_b32_e32 v224, 16, v200
	v_and_b32_e32 v225, 0xffff0000, v200
	v_mul_f32_e32 v168, v50, v224
	v_mul_f32_e32 v169, v51, v225
	v_lshlrev_b32_e32 v224, 16, v201
	v_and_b32_e32 v225, 0xffff0000, v201
	v_mul_f32_e32 v222, v52, v224
	v_mul_f32_e32 v223, v53, v225
	v_lshlrev_b32_e32 v224, 16, v182
	v_and_b32_e32 v225, 0xffff0000, v182
	v_add_f32_e32 v132, v132, v224
	v_add_f32_e32 v133, v133, v225
	v_lshlrev_b32_e32 v224, 16, v183
	v_and_b32_e32 v225, 0xffff0000, v183
	v_add_f32_e32 v164, v164, v224
	v_add_f32_e32 v165, v165, v225
	v_lshlrev_b32_e32 v224, 16, v184
	v_and_b32_e32 v225, 0xffff0000, v184
	v_add_f32_e32 v168, v168, v224
	v_add_f32_e32 v169, v169, v225
	v_lshlrev_b32_e32 v224, 16, v185
	v_and_b32_e32 v225, 0xffff0000, v185
	v_add_f32_e32 v222, v222, v224
	v_add_f32_e32 v223, v223, v225
	v_cvt_pk_bf16_f32 v218, v132, v133
	v_cvt_pk_bf16_f32 v219, v164, v165
	v_cvt_pk_bf16_f32 v220, v168, v169
	v_cvt_pk_bf16_f32 v221, v222, v223
	global_store_dwordx4 v166, v[218:221], s[44:45]
	s_add_u32 s44, s44, 0x2000
	s_addc_u32 s45, s45, 0
	global_load_dwordx4 v[152:155], v166, s[12:13]
	s_add_u32 s12, s12, 0x2000
	s_addc_u32 s13, s13, 0
	global_load_dwordx4 v[182:185], v166, s[20:21]
	s_add_u32 s20, s20, 0x2000
	s_addc_u32 s21, s21, 0
	s_waitcnt vmcnt(12)
	v_lshlrev_b32_e32 v224, 16, v156
	v_and_b32_e32 v225, 0xffff0000, v156
	v_mul_f32_e32 v132, v46, v224
	v_mul_f32_e32 v133, v47, v225
	v_lshlrev_b32_e32 v224, 16, v157
	v_and_b32_e32 v225, 0xffff0000, v157
	v_mul_f32_e32 v164, v48, v224
	v_mul_f32_e32 v165, v49, v225
	v_lshlrev_b32_e32 v224, 16, v158
	v_and_b32_e32 v225, 0xffff0000, v158
	v_mul_f32_e32 v168, v42, v224
	v_mul_f32_e32 v169, v43, v225
	v_lshlrev_b32_e32 v224, 16, v159
	v_and_b32_e32 v225, 0xffff0000, v159
	v_mul_f32_e32 v222, v44, v224
	v_mul_f32_e32 v223, v45, v225
	v_lshlrev_b32_e32 v224, 16, v186
	v_and_b32_e32 v225, 0xffff0000, v186
	v_add_f32_e32 v132, v132, v224
	v_add_f32_e32 v133, v133, v225
	v_lshlrev_b32_e32 v224, 16, v187
	v_and_b32_e32 v225, 0xffff0000, v187
	v_add_f32_e32 v164, v164, v224
	v_add_f32_e32 v165, v165, v225
	v_lshlrev_b32_e32 v224, 16, v188
	v_and_b32_e32 v225, 0xffff0000, v188
	v_add_f32_e32 v168, v168, v224
	v_add_f32_e32 v169, v169, v225
	v_lshlrev_b32_e32 v224, 16, v189
	v_and_b32_e32 v225, 0xffff0000, v189
	v_add_f32_e32 v222, v222, v224
	v_add_f32_e32 v223, v223, v225
	v_cvt_pk_bf16_f32 v214, v132, v133
	v_cvt_pk_bf16_f32 v215, v164, v165
	v_cvt_pk_bf16_f32 v216, v168, v169
	v_cvt_pk_bf16_f32 v217, v222, v223
	global_store_dwordx4 v166, v[214:217], s[44:45]
	s_add_u32 s44, s44, 0x2000
	s_addc_u32 s45, s45, 0
	global_load_dwordx4 v[156:159], v166, s[12:13]
	s_add_u32 s12, s12, 0x2000
	s_addc_u32 s13, s13, 0
	global_load_dwordx4 v[186:189], v166, s[20:21]
	s_add_u32 s20, s20, 0x2000
	s_addc_u32 s21, s21, 0
	s_waitcnt vmcnt(12)
; __device__ __forceinline__ unsigned cvt_pk_bf16(float lo, float hi) { const f32x2 v = {lo, hi}; const bf16x2_t b = __builtin_convertvector(v, bf16x2_t); return __builtin_bit_cast(unsigned, b); }
; __device__ __forceinline__ float bf_lo(unsigned u) { return __uint_as_float(u << 16); }
; __device__ __forceinline__ float bf_hi(unsigned u) { return __uint_as_float(u & 0xffff0000u); }
;     __device__ __forceinline__ void operator()(const f32x4 (&acc)[2][2][4][2], const Unit& u, int wr, int wc, int fr, int fq) const {
;     ...
; #pragma unroll
;         for (int ai = 0; ai < 2; ++ai)
; #pragma unroll
;             for (int bj = 0; bj < 2; ++bj)
; #pragma unroll
;                 for (int m = 0; m < 4; ++m) {
;                     const u32x4 g = *((const u32x4*)Gs + ((size_t)(tile * 16 + (ai * 2 + bj) * 4 + m) * NTHREADS + tid));
;                     f32x4 y0 = acc[ai][bj][m][0], y1 = acc[ai][bj][m][1];
;                     y0[0] *= bf_lo(g.x); y0[1] *= bf_hi(g.x); y0[2] *= bf_lo(g.y); y0[3] *= bf_hi(g.y);
;                     y1[0] *= bf_lo(g.z); y1[1] *= bf_hi(g.z); y1[2] *= bf_lo(g.w); y1[3] *= bf_hi(g.w);
;                     u32x4* sp = (u32x4*)Sb + ((size_t)(tile * 16 + (ai * 2 + bj) * 4 + m) * NTHREADS + tid);
;                     if (br != 0) { const u32x4 t = *sp;
;                         y0[0] += bf_lo(t.x); y0[1] += bf_hi(t.x); y0[2] += bf_lo(t.y); y0[3] += bf_hi(t.y); y1[0] += bf_lo(t.z); y1[1] += bf_hi(t.z); y1[2] += bf_lo(t.w); y1[3] += bf_hi(t.w); }
;                     u32x4 w; w.x = cvt_pk_bf16(y0[0], y0[1]); w.y = cvt_pk_bf16(y0[2], y0[3]); w.z = cvt_pk_bf16(y1[0], y1[1]); w.w = cvt_pk_bf16(y1[2], y1[3]);
;                     if (br != 2) *sp = w;
;                     else {
;                         *(u32x4*)(MIXPRE + (size_t)(row0 + ai * 128 + m * 16) * DM + col00 + bj * 128) = w; }
;                 }
	v_lshlrev_b32_e32 v224, 16, v160
	v_and_b32_e32 v225, 0xffff0000, v160
	v_mul_f32_e32 v132, v38, v224
	v_mul_f32_e32 v133, v39, v225
	v_lshlrev_b32_e32 v224, 16, v161
	v_and_b32_e32 v225, 0xffff0000, v161
	v_mul_f32_e32 v164, v40, v224
	v_mul_f32_e32 v165, v41, v225
	v_lshlrev_b32_e32 v224, 16, v162
	v_and_b32_e32 v225, 0xffff0000, v162
	v_mul_f32_e32 v168, v34, v224
	v_mul_f32_e32 v169, v35, v225
	v_lshlrev_b32_e32 v224, 16, v163
	v_and_b32_e32 v225, 0xffff0000, v163
	v_mul_f32_e32 v222, v36, v224
	v_mul_f32_e32 v223, v37, v225
	v_lshlrev_b32_e32 v224, 16, v202
	v_and_b32_e32 v225, 0xffff0000, v202
	v_add_f32_e32 v132, v132, v224
	v_add_f32_e32 v133, v133, v225
	v_lshlrev_b32_e32 v224, 16, v203
	v_and_b32_e32 v225, 0xffff0000, v203
	v_add_f32_e32 v164, v164, v224
	v_add_f32_e32 v165, v165, v225
	v_lshlrev_b32_e32 v224, 16, v204
	v_and_b32_e32 v225, 0xffff0000, v204
	v_add_f32_e32 v168, v168, v224
	v_add_f32_e32 v169, v169, v225
	v_lshlrev_b32_e32 v224, 16, v205
	v_and_b32_e32 v225, 0xffff0000, v205
	v_add_f32_e32 v222, v222, v224
	v_add_f32_e32 v223, v223, v225
	v_cvt_pk_bf16_f32 v218, v132, v133
	v_cvt_pk_bf16_f32 v219, v164, v165
	v_cvt_pk_bf16_f32 v220, v168, v169
	v_cvt_pk_bf16_f32 v221, v222, v223
	global_store_dwordx4 v166, v[218:221], s[44:45]
	s_add_u32 s44, s44, 0x2000
	s_addc_u32 s45, s45, 0
	global_load_dwordx4 v[160:163], v166, s[12:13]
	s_add_u32 s12, s12, 0x2000
	s_addc_u32 s13, s13, 0
	global_load_dwordx4 v[202:205], v166, s[20:21]
	s_add_u32 s20, s20, 0x2000
	s_addc_u32 s21, s21, 0
	s_waitcnt vmcnt(12)
	v_lshlrev_b32_e32 v224, 16, v174
	v_and_b32_e32 v225, 0xffff0000, v174
	v_mul_f32_e32 v132, v94, v224
	v_mul_f32_e32 v133, v95, v225
	v_lshlrev_b32_e32 v224, 16, v175
	v_and_b32_e32 v225, 0xffff0000, v175
	v_mul_f32_e32 v164, v96, v224
	v_mul_f32_e32 v165, v97, v225
	v_lshlrev_b32_e32 v224, 16, v176
	v_and_b32_e32 v225, 0xffff0000, v176
	v_mul_f32_e32 v168, v90, v224
	v_mul_f32_e32 v169, v91, v225
	v_lshlrev_b32_e32 v224, 16, v177
	v_and_b32_e32 v225, 0xffff0000, v177
	v_mul_f32_e32 v222, v92, v224
	v_mul_f32_e32 v223, v93, v225
	v_lshlrev_b32_e32 v224, 16, v206
	v_and_b32_e32 v225, 0xffff0000, v206
	v_add_f32_e32 v132, v132, v224
	v_add_f32_e32 v133, v133, v225
	v_lshlrev_b32_e32 v224, 16, v207
	v_and_b32_e32 v225, 0xffff0000, v207
	v_add_f32_e32 v164, v164, v224
	v_add_f32_e32 v165, v165, v225
	v_lshlrev_b32_e32 v224, 16, v208
	v_and_b32_e32 v225, 0xffff0000, v208
	v_add_f32_e32 v168, v168, v224
	v_add_f32_e32 v169, v169, v225
	v_lshlrev_b32_e32 v224, 16, v209
	v_and_b32_e32 v225, 0xffff0000, v209
	v_add_f32_e32 v222, v222, v224
	v_add_f32_e32 v223, v223, v225
	v_cvt_pk_bf16_f32 v214, v132, v133
	v_cvt_pk_bf16_f32 v215, v164, v165
	v_cvt_pk_bf16_f32 v216, v168, v169
	v_cvt_pk_bf16_f32 v217, v222, v223
	global_store_dwordx4 v166, v[214:217], s[44:45]
	s_add_u32 s44, s44, 0x2000
	s_addc_u32 s45, s45, 0
	global_load_dwordx4 v[174:177], v166, s[12:13]
	s_add_u32 s12, s12, 0x2000
	s_addc_u32 s13, s13, 0
	global_load_dwordx4 v[206:209], v166, s[20:21]
	s_add_u32 s20, s20, 0x2000
	s_addc_u32 s21, s21, 0
	s_waitcnt vmcnt(12)
	v_lshlrev_b32_e32 v224, 16, v178
	v_and_b32_e32 v225, 0xffff0000, v178
	v_mul_f32_e32 v132, v86, v224
	v_mul_f32_e32 v133, v87, v225
	v_lshlrev_b32_e32 v224, 16, v179
	v_and_b32_e32 v225, 0xffff0000, v179
	v_mul_f32_e32 v164, v88, v224
	v_mul_f32_e32 v165, v89, v225
	v_lshlrev_b32_e32 v224, 16, v180
	v_and_b32_e32 v225, 0xffff0000, v180
	v_mul_f32_e32 v168, v82, v224
	v_mul_f32_e32 v169, v83, v225
	v_lshlrev_b32_e32 v224, 16, v181
	v_and_b32_e32 v225, 0xffff0000, v181
	v_mul_f32_e32 v222, v84, v224
	v_mul_f32_e32 v223, v85, v225
	v_lshlrev_b32_e32 v224, 16, v210
	v_and_b32_e32 v225, 0xffff0000, v210
	v_add_f32_e32 v132, v132, v224
	v_add_f32_e32 v133, v133, v225
	v_lshlrev_b32_e32 v224, 16, v211
	v_and_b32_e32 v225, 0xffff0000, v211
	v_add_f32_e32 v164, v164, v224
	v_add_f32_e32 v165, v165, v225
	v_lshlrev_b32_e32 v224, 16, v212
	v_and_b32_e32 v225, 0xffff0000, v212
	v_add_f32_e32 v168, v168, v224
	v_add_f32_e32 v169, v169, v225
	v_lshlrev_b32_e32 v224, 16, v213
	v_and_b32_e32 v225, 0xffff0000, v213
	v_add_f32_e32 v222, v222, v224
	v_add_f32_e32 v223, v223, v225
	v_cvt_pk_bf16_f32 v218, v132, v133
	v_cvt_pk_bf16_f32 v219, v164, v165
	v_cvt_pk_bf16_f32 v220, v168, v169
	v_cvt_pk_bf16_f32 v221, v222, v223
	global_store_dwordx4 v166, v[218:221], s[44:45]
	s_add_u32 s44, s44, 0x2000
	s_addc_u32 s45, s45, 0
	global_load_dwordx4 v[178:181], v166, s[12:13]
	s_add_u32 s12, s12, 0x2000
	s_addc_u32 s13, s13, 0
	global_load_dwordx4 v[210:213], v166, s[20:21]
	s_add_u32 s20, s20, 0x2000
	s_addc_u32 s21, s21, 0
	s_waitcnt vmcnt(12)
	v_lshlrev_b32_e32 v224, 16, v152
	v_and_b32_e32 v225, 0xffff0000, v152
	v_mul_f32_e32 v132, v78, v224
	v_mul_f32_e32 v133, v79, v225
	v_lshlrev_b32_e32 v224, 16, v153
	v_and_b32_e32 v225, 0xffff0000, v153
	v_mul_f32_e32 v164, v80, v224
	v_mul_f32_e32 v165, v81, v225
	v_lshlrev_b32_e32 v224, 16, v154
	v_and_b32_e32 v225, 0xffff0000, v154
	v_mul_f32_e32 v168, v74, v224
	v_mul_f32_e32 v169, v75, v225
	v_lshlrev_b32_e32 v224, 16, v155
	v_and_b32_e32 v225, 0xffff0000, v155
	v_mul_f32_e32 v222, v76, v224
	v_mul_f32_e32 v223, v77, v225
	v_lshlrev_b32_e32 v224, 16, v182
	v_and_b32_e32 v225, 0xffff0000, v182
	v_add_f32_e32 v132, v132, v224
	v_add_f32_e32 v133, v133, v225
	v_lshlrev_b32_e32 v224, 16, v183
	v_and_b32_e32 v225, 0xffff0000, v183
	v_add_f32_e32 v164, v164, v224
	v_add_f32_e32 v165, v165, v225
	v_lshlrev_b32_e32 v224, 16, v184
	v_and_b32_e32 v225, 0xffff0000, v184
	v_add_f32_e32 v168, v168, v224
	v_add_f32_e32 v169, v169, v225
	v_lshlrev_b32_e32 v224, 16, v185
	v_and_b32_e32 v225, 0xffff0000, v185
	v_add_f32_e32 v222, v222, v224
	v_add_f32_e32 v223, v223, v225
	v_cvt_pk_bf16_f32 v214, v132, v133
	v_cvt_pk_bf16_f32 v215, v164, v165
	v_cvt_pk_bf16_f32 v216, v168, v169
	v_cvt_pk_bf16_f32 v217, v222, v223
	global_store_dwordx4 v166, v[214:217], s[44:45]
	s_add_u32 s44, s44, 0x2000
	s_addc_u32 s45, s45, 0
	global_load_dwordx4 v[152:155], v166, s[12:13]
	s_add_u32 s12, s12, 0x2000
	s_addc_u32 s13, s13, 0
	global_load_dwordx4 v[182:185], v166, s[20:21]
	s_add_u32 s20, s20, 0x2000
	s_addc_u32 s21, s21, 0
	s_waitcnt vmcnt(12)
; __device__ __forceinline__ unsigned cvt_pk_bf16(float lo, float hi) { const f32x2 v = {lo, hi}; const bf16x2_t b = __builtin_convertvector(v, bf16x2_t); return __builtin_bit_cast(unsigned, b); }
; __device__ __forceinline__ float bf_lo(unsigned u) { return __uint_as_float(u << 16); }
; __device__ __forceinline__ float bf_hi(unsigned u) { return __uint_as_float(u & 0xffff0000u); }
;     __device__ __forceinline__ void operator()(const f32x4 (&acc)[2][2][4][2], const Unit& u, int wr, int wc, int fr, int fq) const {
;     ...
; #pragma unroll
;         for (int ai = 0; ai < 2; ++ai)
; #pragma unroll
;             for (int bj = 0; bj < 2; ++bj)
; #pragma unroll
;                 for (int m = 0; m < 4; ++m) {
;                     const u32x4 g = *((const u32x4*)Gs + ((size_t)(tile * 16 + (ai * 2 + bj) * 4 + m) * NTHREADS + tid));
;                     f32x4 y0 = acc[ai][bj][m][0], y1 = acc[ai][bj][m][1];
;                     y0[0] *= bf_lo(g.x); y0[1] *= bf_hi(g.x); y0[2] *= bf_lo(g.y); y0[3] *= bf_hi(g.y);
;                     y1[0] *= bf_lo(g.z); y1[1] *= bf_hi(g.z); y1[2] *= bf_lo(g.w); y1[3] *= bf_hi(g.w);
;                     u32x4* sp = (u32x4*)Sb + ((size_t)(tile * 16 + (ai * 2 + bj) * 4 + m) * NTHREADS + tid);
;                     if (br != 0) { const u32x4 t = *sp;
;                         y0[0] += bf_lo(t.x); y0[1] += bf_hi(t.x); y0[2] += bf_lo(t.y); y0[3] += bf_hi(t.y); y1[0] += bf_lo(t.z); y1[1] += bf_hi(t.z); y1[2] += bf_lo(t.w); y1[3] += bf_hi(t.w); }
;                     u32x4 w; w.x = cvt_pk_bf16(y0[0], y0[1]); w.y = cvt_pk_bf16(y0[2], y0[3]); w.z = cvt_pk_bf16(y1[0], y1[1]); w.w = cvt_pk_bf16(y1[2], y1[3]);
;                     if (br != 2) *sp = w;
;                     else {
;                         *(u32x4*)(MIXPRE + (size_t)(row0 + ai * 128 + m * 16) * DM + col00 + bj * 128) = w; }
;                 }
	v_lshlrev_b32_e32 v224, 16, v156
	v_and_b32_e32 v225, 0xffff0000, v156
	v_mul_f32_e32 v132, v70, v224
	v_mul_f32_e32 v133, v71, v225
	v_lshlrev_b32_e32 v224, 16, v157
	v_and_b32_e32 v225, 0xffff0000, v157
	v_mul_f32_e32 v164, v72, v224
	v_mul_f32_e32 v165, v73, v225
	v_lshlrev_b32_e32 v224, 16, v158
	v_and_b32_e32 v225, 0xffff0000, v158
	v_mul_f32_e32 v168, v66, v224
	v_mul_f32_e32 v169, v67, v225
	v_lshlrev_b32_e32 v224, 16, v159
	v_and_b32_e32 v225, 0xffff0000, v159
	v_mul_f32_e32 v222, v68, v224
	v_mul_f32_e32 v223, v69, v225
	v_lshlrev_b32_e32 v224, 16, v186
	v_and_b32_e32 v225, 0xffff0000, v186
	v_add_f32_e32 v132, v132, v224
	v_add_f32_e32 v133, v133, v225
	v_lshlrev_b32_e32 v224, 16, v187
	v_and_b32_e32 v225, 0xffff0000, v187
	v_add_f32_e32 v164, v164, v224
	v_add_f32_e32 v165, v165, v225
	v_lshlrev_b32_e32 v224, 16, v188
	v_and_b32_e32 v225, 0xffff0000, v188
	v_add_f32_e32 v168, v168, v224
	v_add_f32_e32 v169, v169, v225
	v_lshlrev_b32_e32 v224, 16, v189
	v_and_b32_e32 v225, 0xffff0000, v189
	v_add_f32_e32 v222, v222, v224
	v_add_f32_e32 v223, v223, v225
	v_cvt_pk_bf16_f32 v218, v132, v133
	v_cvt_pk_bf16_f32 v219, v164, v165
	v_cvt_pk_bf16_f32 v220, v168, v169
	v_cvt_pk_bf16_f32 v221, v222, v223
	global_store_dwordx4 v166, v[218:221], s[44:45]
	s_add_u32 s44, s44, 0x2000
	s_addc_u32 s45, s45, 0
	s_waitcnt vmcnt(10)
	v_lshlrev_b32_e32 v224, 16, v160
	v_and_b32_e32 v225, 0xffff0000, v160
	v_mul_f32_e32 v132, v30, v224
	v_mul_f32_e32 v133, v31, v225
	v_lshlrev_b32_e32 v224, 16, v161
	v_and_b32_e32 v225, 0xffff0000, v161
	v_mul_f32_e32 v164, v32, v224
	v_mul_f32_e32 v165, v33, v225
	v_lshlrev_b32_e32 v224, 16, v162
	v_and_b32_e32 v225, 0xffff0000, v162
	v_mul_f32_e32 v168, v26, v224
	v_mul_f32_e32 v169, v27, v225
	v_lshlrev_b32_e32 v224, 16, v163
	v_and_b32_e32 v225, 0xffff0000, v163
	v_mul_f32_e32 v222, v28, v224
	v_mul_f32_e32 v223, v29, v225
	v_lshlrev_b32_e32 v224, 16, v202
	v_and_b32_e32 v225, 0xffff0000, v202
	v_add_f32_e32 v132, v132, v224
	v_add_f32_e32 v133, v133, v225
	v_lshlrev_b32_e32 v224, 16, v203
	v_and_b32_e32 v225, 0xffff0000, v203
	v_add_f32_e32 v164, v164, v224
	v_add_f32_e32 v165, v165, v225
	v_lshlrev_b32_e32 v224, 16, v204
	v_and_b32_e32 v225, 0xffff0000, v204
	v_add_f32_e32 v168, v168, v224
	v_add_f32_e32 v169, v169, v225
	v_lshlrev_b32_e32 v224, 16, v205
	v_and_b32_e32 v225, 0xffff0000, v205
	v_add_f32_e32 v222, v222, v224
	v_add_f32_e32 v223, v223, v225
	v_cvt_pk_bf16_f32 v214, v132, v133
	v_cvt_pk_bf16_f32 v215, v164, v165
	v_cvt_pk_bf16_f32 v216, v168, v169
	v_cvt_pk_bf16_f32 v217, v222, v223
	global_store_dwordx4 v166, v[214:217], s[44:45]
	s_add_u32 s44, s44, 0x2000
	s_addc_u32 s45, s45, 0
	s_waitcnt vmcnt(8)
	v_lshlrev_b32_e32 v224, 16, v174
	v_and_b32_e32 v225, 0xffff0000, v174
	v_mul_f32_e32 v132, v22, v224
	v_mul_f32_e32 v133, v23, v225
	v_lshlrev_b32_e32 v224, 16, v175
	v_and_b32_e32 v225, 0xffff0000, v175
	v_mul_f32_e32 v164, v24, v224
	v_mul_f32_e32 v165, v25, v225
	v_lshlrev_b32_e32 v224, 16, v176
	v_and_b32_e32 v225, 0xffff0000, v176
	v_mul_f32_e32 v168, v18, v224
	v_mul_f32_e32 v169, v19, v225
	v_lshlrev_b32_e32 v224, 16, v177
	v_and_b32_e32 v225, 0xffff0000, v177
	v_mul_f32_e32 v222, v20, v224
	v_mul_f32_e32 v223, v21, v225
	v_lshlrev_b32_e32 v224, 16, v206
	v_and_b32_e32 v225, 0xffff0000, v206
	v_add_f32_e32 v132, v132, v224
	v_add_f32_e32 v133, v133, v225
	v_lshlrev_b32_e32 v224, 16, v207
	v_and_b32_e32 v225, 0xffff0000, v207
	v_add_f32_e32 v164, v164, v224
	v_add_f32_e32 v165, v165, v225
	v_lshlrev_b32_e32 v224, 16, v208
	v_and_b32_e32 v225, 0xffff0000, v208
	v_add_f32_e32 v168, v168, v224
	v_add_f32_e32 v169, v169, v225
	v_lshlrev_b32_e32 v224, 16, v209
	v_and_b32_e32 v225, 0xffff0000, v209
	v_add_f32_e32 v222, v222, v224
	v_add_f32_e32 v223, v223, v225
	v_cvt_pk_bf16_f32 v218, v132, v133
	v_cvt_pk_bf16_f32 v219, v164, v165
	v_cvt_pk_bf16_f32 v220, v168, v169
	v_cvt_pk_bf16_f32 v221, v222, v223
	global_store_dwordx4 v166, v[218:221], s[44:45]
	s_add_u32 s44, s44, 0x2000
	s_addc_u32 s45, s45, 0
	s_waitcnt vmcnt(6)
	v_lshlrev_b32_e32 v224, 16, v178
	v_and_b32_e32 v225, 0xffff0000, v178
	v_mul_f32_e32 v132, v14, v224
	v_mul_f32_e32 v133, v15, v225
	v_lshlrev_b32_e32 v224, 16, v179
	v_and_b32_e32 v225, 0xffff0000, v179
	v_mul_f32_e32 v164, v16, v224
	v_mul_f32_e32 v165, v17, v225
	v_lshlrev_b32_e32 v224, 16, v180
	v_and_b32_e32 v225, 0xffff0000, v180
	v_mul_f32_e32 v168, v10, v224
	v_mul_f32_e32 v169, v11, v225
	v_lshlrev_b32_e32 v224, 16, v181
	v_and_b32_e32 v225, 0xffff0000, v181
	v_mul_f32_e32 v222, v12, v224
	v_mul_f32_e32 v223, v13, v225
	v_lshlrev_b32_e32 v224, 16, v210
	v_and_b32_e32 v225, 0xffff0000, v210
	v_add_f32_e32 v132, v132, v224
	v_add_f32_e32 v133, v133, v225
	v_lshlrev_b32_e32 v224, 16, v211
	v_and_b32_e32 v225, 0xffff0000, v211
	v_add_f32_e32 v164, v164, v224
	v_add_f32_e32 v165, v165, v225
	v_lshlrev_b32_e32 v224, 16, v212
	v_and_b32_e32 v225, 0xffff0000, v212
	v_add_f32_e32 v168, v168, v224
	v_add_f32_e32 v169, v169, v225
	v_lshlrev_b32_e32 v224, 16, v213
	v_and_b32_e32 v225, 0xffff0000, v213
	v_add_f32_e32 v222, v222, v224
	v_add_f32_e32 v223, v223, v225
	v_cvt_pk_bf16_f32 v214, v132, v133
	v_cvt_pk_bf16_f32 v215, v164, v165
	v_cvt_pk_bf16_f32 v216, v168, v169
	v_cvt_pk_bf16_f32 v217, v222, v223
	global_store_dwordx4 v166, v[214:217], s[44:45]
	s_add_u32 s44, s44, 0x2000
	s_addc_u32 s45, s45, 0
	s_waitcnt vmcnt(4)
	v_lshlrev_b32_e32 v224, 16, v152
	v_and_b32_e32 v225, 0xffff0000, v152
	v_mul_f32_e32 v132, v6, v224
	v_mul_f32_e32 v133, v7, v225
	v_lshlrev_b32_e32 v224, 16, v153
	v_and_b32_e32 v225, 0xffff0000, v153
	v_mul_f32_e32 v164, v8, v224
	v_mul_f32_e32 v165, v9, v225
	v_lshlrev_b32_e32 v224, 16, v154
	v_and_b32_e32 v225, 0xffff0000, v154
	v_mul_f32_e32 v168, v2, v224
	v_mul_f32_e32 v169, v3, v225
	v_lshlrev_b32_e32 v224, 16, v155
	v_and_b32_e32 v225, 0xffff0000, v155
	v_mul_f32_e32 v222, v4, v224
	v_mul_f32_e32 v223, v5, v225
	v_lshlrev_b32_e32 v224, 16, v182
	v_and_b32_e32 v225, 0xffff0000, v182
	v_add_f32_e32 v132, v132, v224
	v_add_f32_e32 v133, v133, v225
	v_lshlrev_b32_e32 v224, 16, v183
	v_and_b32_e32 v225, 0xffff0000, v183
	v_add_f32_e32 v164, v164, v224
	v_add_f32_e32 v165, v165, v225
	v_lshlrev_b32_e32 v224, 16, v184
	v_and_b32_e32 v225, 0xffff0000, v184
	v_add_f32_e32 v168, v168, v224
	v_add_f32_e32 v169, v169, v225
	v_lshlrev_b32_e32 v224, 16, v185
	v_and_b32_e32 v225, 0xffff0000, v185
	v_add_f32_e32 v222, v222, v224
	v_add_f32_e32 v223, v223, v225
	v_cvt_pk_bf16_f32 v218, v132, v133
	v_cvt_pk_bf16_f32 v219, v164, v165
	v_cvt_pk_bf16_f32 v220, v168, v169
	v_cvt_pk_bf16_f32 v221, v222, v223
	global_store_dwordx4 v166, v[218:221], s[44:45]
	s_add_u32 s44, s44, 0x2000
	s_addc_u32 s45, s45, 0
	s_branch .LBB0_304
; __device__ __forceinline__ unsigned cvt_pk_bf16(float lo, float hi) { const f32x2 v = {lo, hi}; const bf16x2_t b = __builtin_convertvector(v, bf16x2_t); return __builtin_bit_cast(unsigned, b); }
; __device__ __forceinline__ float bf_lo(unsigned u) { return __uint_as_float(u << 16); }
; __device__ __forceinline__ float bf_hi(unsigned u) { return __uint_as_float(u & 0xffff0000u); }
;     __device__ __forceinline__ void operator()(const f32x4 (&acc)[2][2][4][2], const Unit& u, int wr, int wc, int fr, int fq) const {
;     ...
; #pragma unroll
;         for (int ai = 0; ai < 2; ++ai)
; #pragma unroll
;             for (int bj = 0; bj < 2; ++bj)
; #pragma unroll
;                 for (int m = 0; m < 4; ++m) {
;                     const u32x4 g = *((const u32x4*)Gs + ((size_t)(tile * 16 + (ai * 2 + bj) * 4 + m) * NTHREADS + tid));
;                     f32x4 y0 = acc[ai][bj][m][0], y1 = acc[ai][bj][m][1];
;                     y0[0] *= bf_lo(g.x); y0[1] *= bf_hi(g.x); y0[2] *= bf_lo(g.y); y0[3] *= bf_hi(g.y);
;                     y1[0] *= bf_lo(g.z); y1[1] *= bf_hi(g.z); y1[2] *= bf_lo(g.w); y1[3] *= bf_hi(g.w);
;                     u32x4* sp = (u32x4*)Sb + ((size_t)(tile * 16 + (ai * 2 + bj) * 4 + m) * NTHREADS + tid);
;                     if (br != 0) { const u32x4 t = *sp;
;                         y0[0] += bf_lo(t.x); y0[1] += bf_hi(t.x); y0[2] += bf_lo(t.y); y0[3] += bf_hi(t.y); y1[0] += bf_lo(t.z); y1[1] += bf_hi(t.z); y1[2] += bf_lo(t.w); y1[3] += bf_hi(t.w); }
;                     u32x4 w; w.x = cvt_pk_bf16(y0[0], y0[1]); w.y = cvt_pk_bf16(y0[2], y0[3]); w.z = cvt_pk_bf16(y1[0], y1[1]); w.w = cvt_pk_bf16(y1[2], y1[3]);
;                     if (br != 2) *sp = w;
;                     else {
;                         *(u32x4*)(MIXPRE + (size_t)(row0 + ai * 128 + m * 16) * DM + col00 + bj * 128) = w; }
;                 }
.Lpl_br0:
	s_add_u32 s12, s12, 0x2000
	s_addc_u32 s13, s13, 0
	s_add_u32 s12, s12, 0x2000
	s_addc_u32 s13, s13, 0
	s_add_u32 s12, s12, 0x2000
	s_addc_u32 s13, s13, 0
	s_add_u32 s12, s12, 0x2000
	s_addc_u32 s13, s13, 0
	s_add_u32 s12, s12, 0x2000
	s_addc_u32 s13, s13, 0
	v_lshlrev_b32_e32 v224, 16, v230
	v_and_b32_e32 v225, 0xffff0000, v230
	v_mul_f32_e32 v132, v126, v224
	v_mul_f32_e32 v133, v127, v225
	v_lshlrev_b32_e32 v224, 16, v231
	v_and_b32_e32 v225, 0xffff0000, v231
	v_mul_f32_e32 v164, v128, v224
	v_mul_f32_e32 v165, v129, v225
	v_lshlrev_b32_e32 v224, 16, v232
	v_and_b32_e32 v225, 0xffff0000, v232
	v_mul_f32_e32 v168, v122, v224
	v_mul_f32_e32 v169, v123, v225
	v_lshlrev_b32_e32 v224, 16, v233
	v_and_b32_e32 v225, 0xffff0000, v233
	v_mul_f32_e32 v222, v124, v224
	v_mul_f32_e32 v223, v125, v225
	v_cvt_pk_bf16_f32 v214, v132, v133
	v_cvt_pk_bf16_f32 v215, v164, v165
	v_cvt_pk_bf16_f32 v216, v168, v169
	v_cvt_pk_bf16_f32 v217, v222, v223
	global_store_dwordx4 v166, v[214:217], s[44:45]
	s_add_u32 s44, s44, 0x2000
	s_addc_u32 s45, s45, 0
	s_add_u32 s12, s12, 0x2000
	s_addc_u32 s13, s13, 0
	v_lshlrev_b32_e32 v224, 16, v234
	v_and_b32_e32 v225, 0xffff0000, v234
	v_mul_f32_e32 v132, v118, v224
	v_mul_f32_e32 v133, v119, v225
	v_lshlrev_b32_e32 v224, 16, v235
	v_and_b32_e32 v225, 0xffff0000, v235
	v_mul_f32_e32 v164, v120, v224
	v_mul_f32_e32 v165, v121, v225
	v_lshlrev_b32_e32 v224, 16, v236
	v_and_b32_e32 v225, 0xffff0000, v236
	v_mul_f32_e32 v168, v114, v224
	v_mul_f32_e32 v169, v115, v225
	v_lshlrev_b32_e32 v224, 16, v237
	v_and_b32_e32 v225, 0xffff0000, v237
	v_mul_f32_e32 v222, v116, v224
	v_mul_f32_e32 v223, v117, v225
	v_cvt_pk_bf16_f32 v218, v132, v133
	v_cvt_pk_bf16_f32 v219, v164, v165
	v_cvt_pk_bf16_f32 v220, v168, v169
	v_cvt_pk_bf16_f32 v221, v222, v223
	global_store_dwordx4 v166, v[218:221], s[44:45]
	s_add_u32 s44, s44, 0x2000
	s_addc_u32 s45, s45, 0
	global_load_dwordx4 v[156:159], v166, s[12:13]
	s_add_u32 s12, s12, 0x2000
	s_addc_u32 s13, s13, 0
	v_lshlrev_b32_e32 v224, 16, v238
	v_and_b32_e32 v225, 0xffff0000, v238
	v_mul_f32_e32 v132, v110, v224
	v_mul_f32_e32 v133, v111, v225
	v_lshlrev_b32_e32 v224, 16, v239
	v_and_b32_e32 v225, 0xffff0000, v239
	v_mul_f32_e32 v164, v112, v224
	v_mul_f32_e32 v165, v113, v225
	v_lshlrev_b32_e32 v224, 16, v240
	v_and_b32_e32 v225, 0xffff0000, v240
	v_mul_f32_e32 v168, v106, v224
	v_mul_f32_e32 v169, v107, v225
	v_lshlrev_b32_e32 v224, 16, v241
	v_and_b32_e32 v225, 0xffff0000, v241
	v_mul_f32_e32 v222, v108, v224
	v_mul_f32_e32 v223, v109, v225
	v_cvt_pk_bf16_f32 v214, v132, v133
	v_cvt_pk_bf16_f32 v215, v164, v165
	v_cvt_pk_bf16_f32 v216, v168, v169
	v_cvt_pk_bf16_f32 v217, v222, v223
	global_store_dwordx4 v166, v[214:217], s[44:45]
	s_add_u32 s44, s44, 0x2000
	s_addc_u32 s45, s45, 0
	global_load_dwordx4 v[160:163], v166, s[12:13]
	s_add_u32 s12, s12, 0x2000
	s_addc_u32 s13, s13, 0
	v_lshlrev_b32_e32 v224, 16, v242
	v_and_b32_e32 v225, 0xffff0000, v242
	v_mul_f32_e32 v132, v102, v224
	v_mul_f32_e32 v133, v103, v225
	v_lshlrev_b32_e32 v224, 16, v243
	v_and_b32_e32 v225, 0xffff0000, v243
	v_mul_f32_e32 v164, v104, v224
	v_mul_f32_e32 v165, v105, v225
	v_lshlrev_b32_e32 v224, 16, v244
	v_and_b32_e32 v225, 0xffff0000, v244
	v_mul_f32_e32 v168, v98, v224
	v_mul_f32_e32 v169, v99, v225
	v_lshlrev_b32_e32 v224, 16, v245
	v_and_b32_e32 v225, 0xffff0000, v245
	v_mul_f32_e32 v222, v100, v224
	v_mul_f32_e32 v223, v101, v225
	v_cvt_pk_bf16_f32 v218, v132, v133
	v_cvt_pk_bf16_f32 v219, v164, v165
	v_cvt_pk_bf16_f32 v220, v168, v169
	v_cvt_pk_bf16_f32 v221, v222, v223
	global_store_dwordx4 v166, v[218:221], s[44:45]
	s_add_u32 s44, s44, 0x2000
	s_addc_u32 s45, s45, 0
	global_load_dwordx4 v[174:177], v166, s[12:13]
	s_add_u32 s12, s12, 0x2000
	s_addc_u32 s13, s13, 0
	v_lshlrev_b32_e32 v224, 16, v246
	v_and_b32_e32 v225, 0xffff0000, v246
	v_mul_f32_e32 v132, v62, v224
	v_mul_f32_e32 v133, v63, v225
	v_lshlrev_b32_e32 v224, 16, v247
	v_and_b32_e32 v225, 0xffff0000, v247
	v_mul_f32_e32 v164, v64, v224
	v_mul_f32_e32 v165, v65, v225
	v_lshlrev_b32_e32 v224, 16, v248
	v_and_b32_e32 v225, 0xffff0000, v248
	v_mul_f32_e32 v168, v58, v224
	v_mul_f32_e32 v169, v59, v225
	v_lshlrev_b32_e32 v224, 16, v249
	v_and_b32_e32 v225, 0xffff0000, v249
	v_mul_f32_e32 v222, v60, v224
	v_mul_f32_e32 v223, v61, v225
	v_cvt_pk_bf16_f32 v214, v132, v133
	v_cvt_pk_bf16_f32 v215, v164, v165
	v_cvt_pk_bf16_f32 v216, v168, v169
	v_cvt_pk_bf16_f32 v217, v222, v223
	global_store_dwordx4 v166, v[214:217], s[44:45]
	s_add_u32 s44, s44, 0x2000
	s_addc_u32 s45, s45, 0
	global_load_dwordx4 v[178:181], v166, s[12:13]
	s_add_u32 s12, s12, 0x2000
	s_addc_u32 s13, s13, 0
	v_lshlrev_b32_e32 v224, 16, v198
	v_and_b32_e32 v225, 0xffff0000, v198
	v_mul_f32_e32 v132, v54, v224
	v_mul_f32_e32 v133, v55, v225
	v_lshlrev_b32_e32 v224, 16, v199
	v_and_b32_e32 v225, 0xffff0000, v199
	v_mul_f32_e32 v164, v56, v224
	v_mul_f32_e32 v165, v57, v225
	v_lshlrev_b32_e32 v224, 16, v200
	v_and_b32_e32 v225, 0xffff0000, v200
	v_mul_f32_e32 v168, v50, v224
	v_mul_f32_e32 v169, v51, v225
	v_lshlrev_b32_e32 v224, 16, v201
	v_and_b32_e32 v225, 0xffff0000, v201
	v_mul_f32_e32 v222, v52, v224
	v_mul_f32_e32 v223, v53, v225
	v_cvt_pk_bf16_f32 v218, v132, v133
	v_cvt_pk_bf16_f32 v219, v164, v165
	v_cvt_pk_bf16_f32 v220, v168, v169
	v_cvt_pk_bf16_f32 v221, v222, v223
	global_store_dwordx4 v166, v[218:221], s[44:45]
	s_add_u32 s44, s44, 0x2000
	s_addc_u32 s45, s45, 0
	global_load_dwordx4 v[152:155], v166, s[12:13]
	s_add_u32 s12, s12, 0x2000
	s_addc_u32 s13, s13, 0
	s_waitcnt vmcnt(8)
; __device__ __forceinline__ unsigned cvt_pk_bf16(float lo, float hi) { const f32x2 v = {lo, hi}; const bf16x2_t b = __builtin_convertvector(v, bf16x2_t); return __builtin_bit_cast(unsigned, b); }
; __device__ __forceinline__ float bf_lo(unsigned u) { return __uint_as_float(u << 16); }
; __device__ __forceinline__ float bf_hi(unsigned u) { return __uint_as_float(u & 0xffff0000u); }
;     __device__ __forceinline__ void operator()(const f32x4 (&acc)[2][2][4][2], const Unit& u, int wr, int wc, int fr, int fq) const {
;     ...
; #pragma unroll
;         for (int ai = 0; ai < 2; ++ai)
; #pragma unroll
;             for (int bj = 0; bj < 2; ++bj)
; #pragma unroll
;                 for (int m = 0; m < 4; ++m) {
;                     const u32x4 g = *((const u32x4*)Gs + ((size_t)(tile * 16 + (ai * 2 + bj) * 4 + m) * NTHREADS + tid));
;                     f32x4 y0 = acc[ai][bj][m][0], y1 = acc[ai][bj][m][1];
;                     y0[0] *= bf_lo(g.x); y0[1] *= bf_hi(g.x); y0[2] *= bf_lo(g.y); y0[3] *= bf_hi(g.y);
;                     y1[0] *= bf_lo(g.z); y1[1] *= bf_hi(g.z); y1[2] *= bf_lo(g.w); y1[3] *= bf_hi(g.w);
;                     u32x4* sp = (u32x4*)Sb + ((size_t)(tile * 16 + (ai * 2 + bj) * 4 + m) * NTHREADS + tid);
;                     if (br != 0) { const u32x4 t = *sp;
;                         y0[0] += bf_lo(t.x); y0[1] += bf_hi(t.x); y0[2] += bf_lo(t.y); y0[3] += bf_hi(t.y); y1[0] += bf_lo(t.z); y1[1] += bf_hi(t.z); y1[2] += bf_lo(t.w); y1[3] += bf_hi(t.w); }
;                     u32x4 w; w.x = cvt_pk_bf16(y0[0], y0[1]); w.y = cvt_pk_bf16(y0[2], y0[3]); w.z = cvt_pk_bf16(y1[0], y1[1]); w.w = cvt_pk_bf16(y1[2], y1[3]);
;                     if (br != 2) *sp = w;
;                     else {
;                         *(u32x4*)(MIXPRE + (size_t)(row0 + ai * 128 + m * 16) * DM + col00 + bj * 128) = w; }
;                 }
	v_lshlrev_b32_e32 v224, 16, v156
	v_and_b32_e32 v225, 0xffff0000, v156
	v_mul_f32_e32 v132, v46, v224
	v_mul_f32_e32 v133, v47, v225
	v_lshlrev_b32_e32 v224, 16, v157
	v_and_b32_e32 v225, 0xffff0000, v157
	v_mul_f32_e32 v164, v48, v224
	v_mul_f32_e32 v165, v49, v225
	v_lshlrev_b32_e32 v224, 16, v158
	v_and_b32_e32 v225, 0xffff0000, v158
	v_mul_f32_e32 v168, v42, v224
	v_mul_f32_e32 v169, v43, v225
	v_lshlrev_b32_e32 v224, 16, v159
	v_and_b32_e32 v225, 0xffff0000, v159
	v_mul_f32_e32 v222, v44, v224
	v_mul_f32_e32 v223, v45, v225
	v_cvt_pk_bf16_f32 v214, v132, v133
	v_cvt_pk_bf16_f32 v215, v164, v165
	v_cvt_pk_bf16_f32 v216, v168, v169
	v_cvt_pk_bf16_f32 v217, v222, v223
	global_store_dwordx4 v166, v[214:217], s[44:45]
	s_add_u32 s44, s44, 0x2000
	s_addc_u32 s45, s45, 0
	global_load_dwordx4 v[156:159], v166, s[12:13]
	s_add_u32 s12, s12, 0x2000
	s_addc_u32 s13, s13, 0
	s_waitcnt vmcnt(8)
	v_lshlrev_b32_e32 v224, 16, v160
	v_and_b32_e32 v225, 0xffff0000, v160
	v_mul_f32_e32 v132, v38, v224
	v_mul_f32_e32 v133, v39, v225
	v_lshlrev_b32_e32 v224, 16, v161
	v_and_b32_e32 v225, 0xffff0000, v161
	v_mul_f32_e32 v164, v40, v224
	v_mul_f32_e32 v165, v41, v225
	v_lshlrev_b32_e32 v224, 16, v162
	v_and_b32_e32 v225, 0xffff0000, v162
	v_mul_f32_e32 v168, v34, v224
	v_mul_f32_e32 v169, v35, v225
	v_lshlrev_b32_e32 v224, 16, v163
	v_and_b32_e32 v225, 0xffff0000, v163
	v_mul_f32_e32 v222, v36, v224
	v_mul_f32_e32 v223, v37, v225
	v_cvt_pk_bf16_f32 v218, v132, v133
	v_cvt_pk_bf16_f32 v219, v164, v165
	v_cvt_pk_bf16_f32 v220, v168, v169
	v_cvt_pk_bf16_f32 v221, v222, v223
	global_store_dwordx4 v166, v[218:221], s[44:45]
	s_add_u32 s44, s44, 0x2000
	s_addc_u32 s45, s45, 0
	global_load_dwordx4 v[160:163], v166, s[12:13]
	s_add_u32 s12, s12, 0x2000
	s_addc_u32 s13, s13, 0
	s_waitcnt vmcnt(8)
	v_lshlrev_b32_e32 v224, 16, v174
	v_and_b32_e32 v225, 0xffff0000, v174
	v_mul_f32_e32 v132, v94, v224
	v_mul_f32_e32 v133, v95, v225
	v_lshlrev_b32_e32 v224, 16, v175
	v_and_b32_e32 v225, 0xffff0000, v175
	v_mul_f32_e32 v164, v96, v224
	v_mul_f32_e32 v165, v97, v225
	v_lshlrev_b32_e32 v224, 16, v176
	v_and_b32_e32 v225, 0xffff0000, v176
	v_mul_f32_e32 v168, v90, v224
	v_mul_f32_e32 v169, v91, v225
	v_lshlrev_b32_e32 v224, 16, v177
	v_and_b32_e32 v225, 0xffff0000, v177
	v_mul_f32_e32 v222, v92, v224
	v_mul_f32_e32 v223, v93, v225
	v_cvt_pk_bf16_f32 v214, v132, v133
	v_cvt_pk_bf16_f32 v215, v164, v165
	v_cvt_pk_bf16_f32 v216, v168, v169
	v_cvt_pk_bf16_f32 v217, v222, v223
	global_store_dwordx4 v166, v[214:217], s[44:45]
	s_add_u32 s44, s44, 0x2000
	s_addc_u32 s45, s45, 0
	global_load_dwordx4 v[174:177], v166, s[12:13]
	s_add_u32 s12, s12, 0x2000
	s_addc_u32 s13, s13, 0
	s_waitcnt vmcnt(8)
	v_lshlrev_b32_e32 v224, 16, v178
	v_and_b32_e32 v225, 0xffff0000, v178
	v_mul_f32_e32 v132, v86, v224
	v_mul_f32_e32 v133, v87, v225
	v_lshlrev_b32_e32 v224, 16, v179
	v_and_b32_e32 v225, 0xffff0000, v179
	v_mul_f32_e32 v164, v88, v224
	v_mul_f32_e32 v165, v89, v225
	v_lshlrev_b32_e32 v224, 16, v180
	v_and_b32_e32 v225, 0xffff0000, v180
	v_mul_f32_e32 v168, v82, v224
	v_mul_f32_e32 v169, v83, v225
	v_lshlrev_b32_e32 v224, 16, v181
	v_and_b32_e32 v225, 0xffff0000, v181
	v_mul_f32_e32 v222, v84, v224
	v_mul_f32_e32 v223, v85, v225
	v_cvt_pk_bf16_f32 v218, v132, v133
	v_cvt_pk_bf16_f32 v219, v164, v165
	v_cvt_pk_bf16_f32 v220, v168, v169
	v_cvt_pk_bf16_f32 v221, v222, v223
	global_store_dwordx4 v166, v[218:221], s[44:45]
	s_add_u32 s44, s44, 0x2000
	s_addc_u32 s45, s45, 0
	global_load_dwordx4 v[178:181], v166, s[12:13]
	s_add_u32 s12, s12, 0x2000
	s_addc_u32 s13, s13, 0
	s_waitcnt vmcnt(8)
	v_lshlrev_b32_e32 v224, 16, v152
	v_and_b32_e32 v225, 0xffff0000, v152
	v_mul_f32_e32 v132, v78, v224
	v_mul_f32_e32 v133, v79, v225
	v_lshlrev_b32_e32 v224, 16, v153
	v_and_b32_e32 v225, 0xffff0000, v153
	v_mul_f32_e32 v164, v80, v224
	v_mul_f32_e32 v165, v81, v225
	v_lshlrev_b32_e32 v224, 16, v154
	v_and_b32_e32 v225, 0xffff0000, v154
	v_mul_f32_e32 v168, v74, v224
	v_mul_f32_e32 v169, v75, v225
	v_lshlrev_b32_e32 v224, 16, v155
	v_and_b32_e32 v225, 0xffff0000, v155
	v_mul_f32_e32 v222, v76, v224
	v_mul_f32_e32 v223, v77, v225
	v_cvt_pk_bf16_f32 v214, v132, v133
	v_cvt_pk_bf16_f32 v215, v164, v165
	v_cvt_pk_bf16_f32 v216, v168, v169
	v_cvt_pk_bf16_f32 v217, v222, v223
	global_store_dwordx4 v166, v[214:217], s[44:45]
	s_add_u32 s44, s44, 0x2000
	s_addc_u32 s45, s45, 0
	global_load_dwordx4 v[152:155], v166, s[12:13]
	s_add_u32 s12, s12, 0x2000
	s_addc_u32 s13, s13, 0
	s_waitcnt vmcnt(8)
	v_lshlrev_b32_e32 v224, 16, v156
	v_and_b32_e32 v225, 0xffff0000, v156
	v_mul_f32_e32 v132, v70, v224
	v_mul_f32_e32 v133, v71, v225
	v_lshlrev_b32_e32 v224, 16, v157
	v_and_b32_e32 v225, 0xffff0000, v157
	v_mul_f32_e32 v164, v72, v224
	v_mul_f32_e32 v165, v73, v225
	v_lshlrev_b32_e32 v224, 16, v158
	v_and_b32_e32 v225, 0xffff0000, v158
	v_mul_f32_e32 v168, v66, v224
	v_mul_f32_e32 v169, v67, v225
	v_lshlrev_b32_e32 v224, 16, v159
	v_and_b32_e32 v225, 0xffff0000, v159
	v_mul_f32_e32 v222, v68, v224
	v_mul_f32_e32 v223, v69, v225
	v_cvt_pk_bf16_f32 v218, v132, v133
	v_cvt_pk_bf16_f32 v219, v164, v165
	v_cvt_pk_bf16_f32 v220, v168, v169
	v_cvt_pk_bf16_f32 v221, v222, v223
	global_store_dwordx4 v166, v[218:221], s[44:45]
	s_add_u32 s44, s44, 0x2000
	s_addc_u32 s45, s45, 0
	s_waitcnt vmcnt(7)
;     __device__ __forceinline__ void operator()(const f32x4 (&acc)[2][2][4][2], const Unit& u, int wr, int wc, int fr, int fq) const {
;     ...
;         if ((u.j & 1) == 0) {
; #pragma unroll
;             for (int bj = 0; bj < 2; ++bj) { const f32x4 b0 = *(const f32x4*)(bgate + br * 1024 + col00 + bj * 128), b1 = *(const f32x4*)(bgate + br * 1024 + col00 + bj * 128 + 4);
; #pragma unroll
;                 for (int ai = 0; ai < 2; ++ai)
; #pragma unroll
;                     for (int m = 0; m < 4; ++m) { f32x4 v0 = acc[ai][bj][m][0] + b0, v1 = acc[ai][bj][m][1] + b1;
; #pragma unroll
;                         for (int i = 0; i < 4; ++i) { v0[i] = fast_sigmoid(v0[i]); v1[i] = fast_sigmoid(v1[i]); }
;                         u32x4 w; w.x = cvt_pk_bf16(v0[0], v0[1]); w.y = cvt_pk_bf16(v0[2], v0[3]); w.z = cvt_pk_bf16(v1[0], v1[1]); w.w = cvt_pk_bf16(v1[2], v1[3]);
;                         *((u32x4*)Gs + ((size_t)(tile * 16 + (ai * 2 + bj) * 4 + m) * NTHREADS + tid)) = w; } }
;     ...
; #pragma unroll
;         for (int ai = 0; ai < 2; ++ai)
; #pragma unroll
;             for (int bj = 0; bj < 2; ++bj)
; #pragma unroll
;                 for (int m = 0; m < 4; ++m) {
;                     const u32x4 g = *((const u32x4*)Gs + ((size_t)(tile * 16 + (ai * 2 + bj) * 4 + m) * NTHREADS + tid));
;                     f32x4 y0 = acc[ai][bj][m][0], y1 = acc[ai][bj][m][1];
;                     y0[0] *= bf_lo(g.x); y0[1] *= bf_hi(g.x); y0[2] *= bf_lo(g.y); y0[3] *= bf_hi(g.y);
;                     y1[0] *= bf_lo(g.z); y1[1] *= bf_hi(g.z); y1[2] *= bf_lo(g.w); y1[3] *= bf_hi(g.w);
;                     u32x4* sp = (u32x4*)Sb + ((size_t)(tile * 16 + (ai * 2 + bj) * 4 + m) * NTHREADS + tid);
;                     if (br != 0) { const u32x4 t = *sp;
;                         y0[0] += bf_lo(t.x); y0[1] += bf_hi(t.x); y0[2] += bf_lo(t.y); y0[3] += bf_hi(t.y); y1[0] += bf_lo(t.z); y1[1] += bf_hi(t.z); y1[2] += bf_lo(t.w); y1[3] += bf_hi(t.w); }
;                     u32x4 w; w.x = cvt_pk_bf16(y0[0], y0[1]); w.y = cvt_pk_bf16(y0[2], y0[3]); w.z = cvt_pk_bf16(y1[0], y1[1]); w.w = cvt_pk_bf16(y1[2], y1[3]);
;                     if (br != 2) *sp = w;
;                     else {
;                         *(u32x4*)(MIXPRE + (size_t)(row0 + ai * 128 + m * 16) * DM + col00 + bj * 128) = w; }
;                 }
	v_lshlrev_b32_e32 v224, 16, v160
	v_and_b32_e32 v225, 0xffff0000, v160
	v_mul_f32_e32 v132, v30, v224
	v_mul_f32_e32 v133, v31, v225
	v_lshlrev_b32_e32 v224, 16, v161
	v_and_b32_e32 v225, 0xffff0000, v161
	v_mul_f32_e32 v164, v32, v224
	v_mul_f32_e32 v165, v33, v225
	v_lshlrev_b32_e32 v224, 16, v162
	v_and_b32_e32 v225, 0xffff0000, v162
	v_mul_f32_e32 v168, v26, v224
	v_mul_f32_e32 v169, v27, v225
	v_lshlrev_b32_e32 v224, 16, v163
	v_and_b32_e32 v225, 0xffff0000, v163
	v_mul_f32_e32 v222, v28, v224
	v_mul_f32_e32 v223, v29, v225
	v_cvt_pk_bf16_f32 v214, v132, v133
	v_cvt_pk_bf16_f32 v215, v164, v165
	v_cvt_pk_bf16_f32 v216, v168, v169
	v_cvt_pk_bf16_f32 v217, v222, v223
	global_store_dwordx4 v166, v[214:217], s[44:45]
	s_add_u32 s44, s44, 0x2000
	s_addc_u32 s45, s45, 0
	s_waitcnt vmcnt(6)
	v_lshlrev_b32_e32 v224, 16, v174
	v_and_b32_e32 v225, 0xffff0000, v174
	v_mul_f32_e32 v132, v22, v224
	v_mul_f32_e32 v133, v23, v225
	v_lshlrev_b32_e32 v224, 16, v175
	v_and_b32_e32 v225, 0xffff0000, v175
	v_mul_f32_e32 v164, v24, v224
	v_mul_f32_e32 v165, v25, v225
	v_lshlrev_b32_e32 v224, 16, v176
	v_and_b32_e32 v225, 0xffff0000, v176
	v_mul_f32_e32 v168, v18, v224
	v_mul_f32_e32 v169, v19, v225
	v_lshlrev_b32_e32 v224, 16, v177
	v_and_b32_e32 v225, 0xffff0000, v177
	v_mul_f32_e32 v222, v20, v224
	v_mul_f32_e32 v223, v21, v225
	v_cvt_pk_bf16_f32 v218, v132, v133
	v_cvt_pk_bf16_f32 v219, v164, v165
	v_cvt_pk_bf16_f32 v220, v168, v169
	v_cvt_pk_bf16_f32 v221, v222, v223
	global_store_dwordx4 v166, v[218:221], s[44:45]
	s_add_u32 s44, s44, 0x2000
	s_addc_u32 s45, s45, 0
	s_waitcnt vmcnt(5)
	v_lshlrev_b32_e32 v224, 16, v178
	v_and_b32_e32 v225, 0xffff0000, v178
	v_mul_f32_e32 v132, v14, v224
	v_mul_f32_e32 v133, v15, v225
	v_lshlrev_b32_e32 v224, 16, v179
	v_and_b32_e32 v225, 0xffff0000, v179
	v_mul_f32_e32 v164, v16, v224
	v_mul_f32_e32 v165, v17, v225
	v_lshlrev_b32_e32 v224, 16, v180
	v_and_b32_e32 v225, 0xffff0000, v180
	v_mul_f32_e32 v168, v10, v224
	v_mul_f32_e32 v169, v11, v225
	v_lshlrev_b32_e32 v224, 16, v181
	v_and_b32_e32 v225, 0xffff0000, v181
	v_mul_f32_e32 v222, v12, v224
	v_mul_f32_e32 v223, v13, v225
	v_cvt_pk_bf16_f32 v214, v132, v133
	v_cvt_pk_bf16_f32 v215, v164, v165
	v_cvt_pk_bf16_f32 v216, v168, v169
	v_cvt_pk_bf16_f32 v217, v222, v223
	global_store_dwordx4 v166, v[214:217], s[44:45]
	s_add_u32 s44, s44, 0x2000
	s_addc_u32 s45, s45, 0
	s_waitcnt vmcnt(4)
	v_lshlrev_b32_e32 v224, 16, v152
	v_and_b32_e32 v225, 0xffff0000, v152
	v_mul_f32_e32 v132, v6, v224
	v_mul_f32_e32 v133, v7, v225
	v_lshlrev_b32_e32 v224, 16, v153
	v_and_b32_e32 v225, 0xffff0000, v153
	v_mul_f32_e32 v164, v8, v224
	v_mul_f32_e32 v165, v9, v225
	v_lshlrev_b32_e32 v224, 16, v154
	v_and_b32_e32 v225, 0xffff0000, v154
	v_mul_f32_e32 v168, v2, v224
	v_mul_f32_e32 v169, v3, v225
	v_lshlrev_b32_e32 v224, 16, v155
	v_and_b32_e32 v225, 0xffff0000, v155
	v_mul_f32_e32 v222, v4, v224
	v_mul_f32_e32 v223, v5, v225
	v_cvt_pk_bf16_f32 v218, v132, v133
	v_cvt_pk_bf16_f32 v219, v164, v165
	v_cvt_pk_bf16_f32 v220, v168, v169
	v_cvt_pk_bf16_f32 v221, v222, v223
	global_store_dwordx4 v166, v[218:221], s[44:45]
	s_add_u32 s44, s44, 0x2000
	s_addc_u32 s45, s45, 0
	s_branch .LBB0_304
.LBB0_402:
	s_lshl_b32 s12, s19, 10
	s_ashr_i32 s13, s12, 31
	s_lshl_b32 s44, s18, 4
	s_lshl_b64 s[12:13], s[12:13], 2
	s_add_u32 s12, s65, s12
	v_ashrrev_i32_e32 v135, 31, v134
	s_addc_u32 s13, s68, s13
	v_lshl_add_u64 v[152:153], v[134:135], 2, s[12:13]
	global_load_dwordx4 v[130:133], v[152:153], off offset:16
	global_load_dwordx4 v[134:137], v[152:153], off
	s_ashr_i32 s45, s44, 31
	s_lshl_b64 s[12:13], s[44:45], 13
	s_waitcnt vmcnt(0)
	v_pk_add_f32 v[124:125], v[124:125], v[132:133]
	v_pk_add_f32 v[122:123], v[122:123], v[130:131]
	v_mul_f32_e32 v124, 0xbfb8aa3b, v124
	v_mul_f32_e32 v122, 0xbfb8aa3b, v122
	v_mul_f32_e32 v123, 0xbfb8aa3b, v123
	v_exp_f32_e32 v122, v122
	v_exp_f32_e32 v123, v123
	v_exp_f32_e32 v124, v124
	v_pk_add_f32 v[128:129], v[128:129], v[136:137]
	v_pk_add_f32 v[126:127], v[126:127], v[134:135]
	v_add_f32_e32 v122, 1.0, v122
	v_add_f32_e32 v123, 1.0, v123
	v_add_f32_e32 v124, 1.0, v124
	v_mul_f32_e32 v126, 0xbfb8aa3b, v126
	v_rcp_f32_e32 v154, v122
	v_mul_f32_e32 v122, 0xbfb8aa3b, v127
	v_rcp_f32_e32 v127, v123
	v_mul_f32_e32 v123, 0xbfb8aa3b, v128
	v_rcp_f32_e32 v128, v124
	v_mul_f32_e32 v124, 0xbfb8aa3b, v129
	v_mul_f32_e32 v125, 0xbfb8aa3b, v125
	v_exp_f32_e32 v126, v126
	v_exp_f32_e32 v122, v122
	v_exp_f32_e32 v123, v123
	v_exp_f32_e32 v124, v124
	v_exp_f32_e32 v125, v125
	v_pk_add_f32 v[116:117], v[116:117], v[132:133]
	v_pk_add_f32 v[114:115], v[114:115], v[130:131]
	v_add_f32_e32 v126, 1.0, v126
	v_add_f32_e32 v122, 1.0, v122
	v_add_f32_e32 v123, 1.0, v123
	v_add_f32_e32 v124, 1.0, v124
	v_add_f32_e32 v125, 1.0, v125
	v_mul_f32_e32 v114, 0xbfb8aa3b, v114
	v_mul_f32_e32 v115, 0xbfb8aa3b, v115
	v_mul_f32_e32 v116, 0xbfb8aa3b, v116
	v_rcp_f32_e32 v126, v126
	v_rcp_f32_e32 v122, v122
	v_rcp_f32_e32 v123, v123
	v_rcp_f32_e32 v124, v124
	v_rcp_f32_e32 v125, v125
	v_exp_f32_e32 v114, v114
	v_exp_f32_e32 v115, v115
	v_exp_f32_e32 v116, v116
	v_cvt_pk_bf16_f32 v122, v126, v122
	v_cvt_pk_bf16_f32 v123, v123, v124
	v_cvt_pk_bf16_f32 v124, v154, v127
	v_cvt_pk_bf16_f32 v125, v128, v125
	v_lshl_add_u64 v[126:127], v[146:147], 0, s[12:13]
	v_pk_add_f32 v[120:121], v[120:121], v[136:137]
	v_pk_add_f32 v[118:119], v[118:119], v[134:135]
	v_add_f32_e32 v114, 1.0, v114
	v_add_f32_e32 v115, 1.0, v115
	v_add_f32_e32 v116, 1.0, v116
	v_mov_b32_e32 v230, v122
	v_mov_b32_e32 v231, v123
	v_mov_b32_e32 v232, v124
	v_mov_b32_e32 v233, v125
	v_mul_f32_e32 v118, 0xbfb8aa3b, v118
; __device__ __forceinline__ unsigned cvt_pk_bf16(float lo, float hi) { const f32x2 v = {lo, hi}; const bf16x2_t b = __builtin_convertvector(v, bf16x2_t); return __builtin_bit_cast(unsigned, b); }
; __device__ __forceinline__ float fast_sigmoid(float x) { return __builtin_amdgcn_rcpf(1.0f + __builtin_amdgcn_exp2f(-x * LOG2E)); }
;     __device__ __forceinline__ void operator()(const f32x4 (&acc)[2][2][4][2], const Unit& u, int wr, int wc, int fr, int fq) const {
;     ...
;         if ((u.j & 1) == 0) {
; #pragma unroll
;             for (int bj = 0; bj < 2; ++bj) { const f32x4 b0 = *(const f32x4*)(bgate + br * 1024 + col00 + bj * 128), b1 = *(const f32x4*)(bgate + br * 1024 + col00 + bj * 128 + 4);
; #pragma unroll
;                 for (int ai = 0; ai < 2; ++ai)
; #pragma unroll
;                     for (int m = 0; m < 4; ++m) { f32x4 v0 = acc[ai][bj][m][0] + b0, v1 = acc[ai][bj][m][1] + b1;
; #pragma unroll
;                         for (int i = 0; i < 4; ++i) { v0[i] = fast_sigmoid(v0[i]); v1[i] = fast_sigmoid(v1[i]); }
;                         u32x4 w; w.x = cvt_pk_bf16(v0[0], v0[1]); w.y = cvt_pk_bf16(v0[2], v0[3]); w.z = cvt_pk_bf16(v1[0], v1[1]); w.w = cvt_pk_bf16(v1[2], v1[3]);
;                         *((u32x4*)Gs + ((size_t)(tile * 16 + (ai * 2 + bj) * 4 + m) * NTHREADS + tid)) = w; } }
	v_mul_f32_e32 v117, 0xbfb8aa3b, v117
	v_rcp_f32_e32 v122, v114
	v_mul_f32_e32 v114, 0xbfb8aa3b, v119
	v_rcp_f32_e32 v119, v115
	v_mul_f32_e32 v115, 0xbfb8aa3b, v120
	v_rcp_f32_e32 v120, v116
	v_mul_f32_e32 v116, 0xbfb8aa3b, v121
	v_exp_f32_e32 v118, v118
	v_exp_f32_e32 v114, v114
	v_exp_f32_e32 v115, v115
	v_exp_f32_e32 v116, v116
	v_exp_f32_e32 v117, v117
	v_pk_add_f32 v[108:109], v[108:109], v[132:133]
	v_pk_add_f32 v[106:107], v[106:107], v[130:131]
	v_add_f32_e32 v118, 1.0, v118
	v_add_f32_e32 v114, 1.0, v114
	v_add_f32_e32 v115, 1.0, v115
	v_add_f32_e32 v116, 1.0, v116
	v_add_f32_e32 v117, 1.0, v117
	v_mul_f32_e32 v106, 0xbfb8aa3b, v106
	v_mul_f32_e32 v107, 0xbfb8aa3b, v107
	v_mul_f32_e32 v108, 0xbfb8aa3b, v108
	v_rcp_f32_e32 v118, v118
	v_rcp_f32_e32 v114, v114
	v_rcp_f32_e32 v115, v115
	v_rcp_f32_e32 v116, v116
	v_rcp_f32_e32 v117, v117
	v_exp_f32_e32 v106, v106
	v_exp_f32_e32 v107, v107
	v_exp_f32_e32 v108, v108
	s_or_b32 s12, s44, 1
	s_ashr_i32 s13, s12, 31
	s_lshl_b64 s[12:13], s[12:13], 13
	v_cvt_pk_bf16_f32 v114, v118, v114
	v_cvt_pk_bf16_f32 v115, v115, v116
	v_cvt_pk_bf16_f32 v116, v122, v119
	v_cvt_pk_bf16_f32 v117, v120, v117
	v_lshl_add_u64 v[118:119], v[146:147], 0, s[12:13]
	v_pk_add_f32 v[112:113], v[112:113], v[136:137]
	v_pk_add_f32 v[110:111], v[110:111], v[134:135]
	v_add_f32_e32 v106, 1.0, v106
	v_add_f32_e32 v107, 1.0, v107
	v_add_f32_e32 v108, 1.0, v108
	v_mov_b32_e32 v234, v114
	v_mov_b32_e32 v235, v115
	v_mov_b32_e32 v236, v116
	v_mov_b32_e32 v237, v117
	v_mul_f32_e32 v110, 0xbfb8aa3b, v110
	v_mul_f32_e32 v109, 0xbfb8aa3b, v109
	v_rcp_f32_e32 v114, v106
	v_mul_f32_e32 v106, 0xbfb8aa3b, v111
	v_rcp_f32_e32 v111, v107
	v_mul_f32_e32 v107, 0xbfb8aa3b, v112
	v_rcp_f32_e32 v112, v108
	v_mul_f32_e32 v108, 0xbfb8aa3b, v113
	v_exp_f32_e32 v110, v110
	v_exp_f32_e32 v106, v106
	v_exp_f32_e32 v107, v107
	v_exp_f32_e32 v108, v108
	v_exp_f32_e32 v109, v109
	v_pk_add_f32 v[100:101], v[100:101], v[132:133]
	v_pk_add_f32 v[98:99], v[98:99], v[130:131]
	v_add_f32_e32 v110, 1.0, v110
	v_add_f32_e32 v106, 1.0, v106
	v_add_f32_e32 v107, 1.0, v107
	v_add_f32_e32 v108, 1.0, v108
	v_add_f32_e32 v109, 1.0, v109
	v_mul_f32_e32 v98, 0xbfb8aa3b, v98
	v_mul_f32_e32 v99, 0xbfb8aa3b, v99
	v_mul_f32_e32 v100, 0xbfb8aa3b, v100
	v_rcp_f32_e32 v110, v110
	v_rcp_f32_e32 v106, v106
	v_rcp_f32_e32 v107, v107
	v_rcp_f32_e32 v108, v108
	v_rcp_f32_e32 v109, v109
	v_exp_f32_e32 v98, v98
	v_exp_f32_e32 v99, v99
	v_exp_f32_e32 v100, v100
	s_or_b32 s12, s44, 2
	s_ashr_i32 s13, s12, 31
	s_lshl_b64 s[12:13], s[12:13], 13
	v_cvt_pk_bf16_f32 v106, v110, v106
	v_cvt_pk_bf16_f32 v107, v107, v108
	v_cvt_pk_bf16_f32 v108, v114, v111
	v_cvt_pk_bf16_f32 v109, v112, v109
	v_lshl_add_u64 v[110:111], v[146:147], 0, s[12:13]
	v_pk_add_f32 v[104:105], v[104:105], v[136:137]
	v_pk_add_f32 v[102:103], v[102:103], v[134:135]
	v_add_f32_e32 v98, 1.0, v98
	v_add_f32_e32 v99, 1.0, v99
	v_add_f32_e32 v100, 1.0, v100
	v_mov_b32_e32 v238, v106
	v_mov_b32_e32 v239, v107
	v_mov_b32_e32 v240, v108
	v_mov_b32_e32 v241, v109
	v_mul_f32_e32 v102, 0xbfb8aa3b, v102
	v_mul_f32_e32 v101, 0xbfb8aa3b, v101
	v_rcp_f32_e32 v106, v98
	v_mul_f32_e32 v98, 0xbfb8aa3b, v103
	v_rcp_f32_e32 v103, v99
	v_mul_f32_e32 v99, 0xbfb8aa3b, v104
	v_rcp_f32_e32 v104, v100
	v_mul_f32_e32 v100, 0xbfb8aa3b, v105
	v_exp_f32_e32 v102, v102
	v_exp_f32_e32 v98, v98
	v_exp_f32_e32 v99, v99
	v_exp_f32_e32 v100, v100
	v_exp_f32_e32 v101, v101
	v_pk_add_f32 v[92:93], v[92:93], v[132:133]
	v_pk_add_f32 v[90:91], v[90:91], v[130:131]
	v_add_f32_e32 v102, 1.0, v102
	v_add_f32_e32 v98, 1.0, v98
	v_add_f32_e32 v99, 1.0, v99
	v_add_f32_e32 v100, 1.0, v100
	v_add_f32_e32 v101, 1.0, v101
	v_mul_f32_e32 v90, 0xbfb8aa3b, v90
	v_mul_f32_e32 v91, 0xbfb8aa3b, v91
	v_mul_f32_e32 v92, 0xbfb8aa3b, v92
	v_rcp_f32_e32 v102, v102
	v_rcp_f32_e32 v98, v98
	v_rcp_f32_e32 v99, v99
	v_rcp_f32_e32 v100, v100
	v_rcp_f32_e32 v101, v101
	v_exp_f32_e32 v90, v90
	v_exp_f32_e32 v91, v91
	v_exp_f32_e32 v92, v92
	s_or_b32 s12, s44, 3
	s_ashr_i32 s13, s12, 31
	s_lshl_b64 s[12:13], s[12:13], 13
	v_cvt_pk_bf16_f32 v98, v102, v98
	v_cvt_pk_bf16_f32 v99, v99, v100
	v_cvt_pk_bf16_f32 v100, v106, v103
	v_cvt_pk_bf16_f32 v101, v104, v101
	v_lshl_add_u64 v[102:103], v[146:147], 0, s[12:13]
	v_pk_add_f32 v[96:97], v[96:97], v[136:137]
	v_pk_add_f32 v[94:95], v[94:95], v[134:135]
	v_add_f32_e32 v90, 1.0, v90
	v_add_f32_e32 v91, 1.0, v91
	v_add_f32_e32 v92, 1.0, v92
	v_mov_b32_e32 v242, v98
	v_mov_b32_e32 v243, v99
	v_mov_b32_e32 v244, v100
	v_mov_b32_e32 v245, v101
	v_mul_f32_e32 v94, 0xbfb8aa3b, v94
	v_mul_f32_e32 v93, 0xbfb8aa3b, v93
	v_rcp_f32_e32 v98, v90
	v_mul_f32_e32 v90, 0xbfb8aa3b, v95
	v_rcp_f32_e32 v95, v91
	v_mul_f32_e32 v91, 0xbfb8aa3b, v96
	v_rcp_f32_e32 v96, v92
	v_mul_f32_e32 v92, 0xbfb8aa3b, v97
	v_exp_f32_e32 v94, v94
	v_exp_f32_e32 v90, v90
	v_exp_f32_e32 v91, v91
	v_exp_f32_e32 v92, v92
	v_exp_f32_e32 v93, v93
	v_pk_add_f32 v[84:85], v[84:85], v[132:133]
	v_pk_add_f32 v[82:83], v[82:83], v[130:131]
	v_add_f32_e32 v94, 1.0, v94
	v_add_f32_e32 v90, 1.0, v90
	v_add_f32_e32 v91, 1.0, v91
	v_add_f32_e32 v92, 1.0, v92
	v_add_f32_e32 v93, 1.0, v93
	v_mul_f32_e32 v82, 0xbfb8aa3b, v82
	v_mul_f32_e32 v83, 0xbfb8aa3b, v83
	v_mul_f32_e32 v84, 0xbfb8aa3b, v84
	v_rcp_f32_e32 v94, v94
	v_rcp_f32_e32 v90, v90
	v_rcp_f32_e32 v91, v91
	v_rcp_f32_e32 v92, v92
	v_rcp_f32_e32 v93, v93
	v_exp_f32_e32 v82, v82
	v_exp_f32_e32 v83, v83
	v_exp_f32_e32 v84, v84
	s_or_b32 s12, s44, 8
	s_ashr_i32 s13, s12, 31
	s_lshl_b64 s[12:13], s[12:13], 13
	v_cvt_pk_bf16_f32 v90, v94, v90
	v_cvt_pk_bf16_f32 v91, v91, v92
	v_cvt_pk_bf16_f32 v92, v98, v95
	v_cvt_pk_bf16_f32 v93, v96, v93
; __device__ __forceinline__ unsigned cvt_pk_bf16(float lo, float hi) { const f32x2 v = {lo, hi}; const bf16x2_t b = __builtin_convertvector(v, bf16x2_t); return __builtin_bit_cast(unsigned, b); }
; __device__ __forceinline__ float fast_sigmoid(float x) { return __builtin_amdgcn_rcpf(1.0f + __builtin_amdgcn_exp2f(-x * LOG2E)); }
;     __device__ __forceinline__ void operator()(const f32x4 (&acc)[2][2][4][2], const Unit& u, int wr, int wc, int fr, int fq) const {
;     ...
;         if ((u.j & 1) == 0) {
; #pragma unroll
;             for (int bj = 0; bj < 2; ++bj) { const f32x4 b0 = *(const f32x4*)(bgate + br * 1024 + col00 + bj * 128), b1 = *(const f32x4*)(bgate + br * 1024 + col00 + bj * 128 + 4);
; #pragma unroll
;                 for (int ai = 0; ai < 2; ++ai)
; #pragma unroll
;                     for (int m = 0; m < 4; ++m) { f32x4 v0 = acc[ai][bj][m][0] + b0, v1 = acc[ai][bj][m][1] + b1;
; #pragma unroll
;                         for (int i = 0; i < 4; ++i) { v0[i] = fast_sigmoid(v0[i]); v1[i] = fast_sigmoid(v1[i]); }
;                         u32x4 w; w.x = cvt_pk_bf16(v0[0], v0[1]); w.y = cvt_pk_bf16(v0[2], v0[3]); w.z = cvt_pk_bf16(v1[0], v1[1]); w.w = cvt_pk_bf16(v1[2], v1[3]);
;                         *((u32x4*)Gs + ((size_t)(tile * 16 + (ai * 2 + bj) * 4 + m) * NTHREADS + tid)) = w; } }
	v_lshl_add_u64 v[94:95], v[146:147], 0, s[12:13]
	v_pk_add_f32 v[88:89], v[88:89], v[136:137]
	v_pk_add_f32 v[86:87], v[86:87], v[134:135]
	v_add_f32_e32 v82, 1.0, v82
	v_add_f32_e32 v83, 1.0, v83
	v_add_f32_e32 v84, 1.0, v84
	global_store_dwordx4 v[94:95], v[90:93], off
	v_mul_f32_e32 v86, 0xbfb8aa3b, v86
	v_mul_f32_e32 v85, 0xbfb8aa3b, v85
	v_rcp_f32_e32 v90, v82
	v_mul_f32_e32 v82, 0xbfb8aa3b, v87
	v_rcp_f32_e32 v87, v83
	v_mul_f32_e32 v83, 0xbfb8aa3b, v88
	v_rcp_f32_e32 v88, v84
	v_mul_f32_e32 v84, 0xbfb8aa3b, v89
	v_exp_f32_e32 v86, v86
	v_exp_f32_e32 v82, v82
	v_exp_f32_e32 v83, v83
	v_exp_f32_e32 v84, v84
	v_exp_f32_e32 v85, v85
	v_pk_add_f32 v[76:77], v[76:77], v[132:133]
	v_pk_add_f32 v[74:75], v[74:75], v[130:131]
	v_add_f32_e32 v86, 1.0, v86
	v_add_f32_e32 v82, 1.0, v82
	v_add_f32_e32 v83, 1.0, v83
	v_add_f32_e32 v84, 1.0, v84
	v_add_f32_e32 v85, 1.0, v85
	v_mul_f32_e32 v74, 0xbfb8aa3b, v74
	v_mul_f32_e32 v75, 0xbfb8aa3b, v75
	v_mul_f32_e32 v76, 0xbfb8aa3b, v76
	v_rcp_f32_e32 v86, v86
	v_rcp_f32_e32 v82, v82
	v_rcp_f32_e32 v83, v83
	v_rcp_f32_e32 v84, v84
	v_rcp_f32_e32 v85, v85
	v_exp_f32_e32 v74, v74
	v_exp_f32_e32 v75, v75
	v_exp_f32_e32 v76, v76
	s_or_b32 s12, s44, 9
	s_ashr_i32 s13, s12, 31
	s_lshl_b64 s[12:13], s[12:13], 13
	v_cvt_pk_bf16_f32 v82, v86, v82
	v_cvt_pk_bf16_f32 v83, v83, v84
	v_cvt_pk_bf16_f32 v84, v90, v87
	v_cvt_pk_bf16_f32 v85, v88, v85
	v_lshl_add_u64 v[86:87], v[146:147], 0, s[12:13]
	v_pk_add_f32 v[80:81], v[80:81], v[136:137]
	v_pk_add_f32 v[78:79], v[78:79], v[134:135]
	v_add_f32_e32 v74, 1.0, v74
	v_add_f32_e32 v75, 1.0, v75
	v_add_f32_e32 v76, 1.0, v76
	global_store_dwordx4 v[86:87], v[82:85], off
	v_mul_f32_e32 v78, 0xbfb8aa3b, v78
	v_mul_f32_e32 v77, 0xbfb8aa3b, v77
	v_rcp_f32_e32 v82, v74
	v_mul_f32_e32 v74, 0xbfb8aa3b, v79
	v_rcp_f32_e32 v79, v75
	v_mul_f32_e32 v75, 0xbfb8aa3b, v80
	v_rcp_f32_e32 v80, v76
	v_mul_f32_e32 v76, 0xbfb8aa3b, v81
	v_exp_f32_e32 v78, v78
	v_exp_f32_e32 v74, v74
	v_exp_f32_e32 v75, v75
	v_exp_f32_e32 v76, v76
	v_exp_f32_e32 v77, v77
	v_pk_add_f32 v[68:69], v[68:69], v[132:133]
	v_pk_add_f32 v[66:67], v[66:67], v[130:131]
	v_add_f32_e32 v78, 1.0, v78
	v_add_f32_e32 v74, 1.0, v74
	v_add_f32_e32 v75, 1.0, v75
	v_add_f32_e32 v76, 1.0, v76
	v_add_f32_e32 v77, 1.0, v77
	v_mul_f32_e32 v66, 0xbfb8aa3b, v66
	v_mul_f32_e32 v67, 0xbfb8aa3b, v67
	v_mul_f32_e32 v68, 0xbfb8aa3b, v68
	v_rcp_f32_e32 v78, v78
	v_rcp_f32_e32 v74, v74
	v_rcp_f32_e32 v75, v75
	v_rcp_f32_e32 v76, v76
	v_rcp_f32_e32 v77, v77
	v_exp_f32_e32 v66, v66
	v_exp_f32_e32 v67, v67
	v_exp_f32_e32 v68, v68
	s_or_b32 s12, s44, 10
	s_ashr_i32 s13, s12, 31
	s_lshl_b64 s[12:13], s[12:13], 13
	v_cvt_pk_bf16_f32 v74, v78, v74
	v_cvt_pk_bf16_f32 v75, v75, v76
	v_cvt_pk_bf16_f32 v76, v82, v79
	v_cvt_pk_bf16_f32 v77, v80, v77
	v_lshl_add_u64 v[78:79], v[146:147], 0, s[12:13]
	v_pk_add_f32 v[72:73], v[72:73], v[136:137]
	v_pk_add_f32 v[70:71], v[70:71], v[134:135]
	v_add_f32_e32 v66, 1.0, v66
	v_add_f32_e32 v67, 1.0, v67
	v_add_f32_e32 v68, 1.0, v68
	global_store_dwordx4 v[78:79], v[74:77], off
	v_mul_f32_e32 v70, 0xbfb8aa3b, v70
	v_mul_f32_e32 v69, 0xbfb8aa3b, v69
	v_rcp_f32_e32 v74, v66
	v_mul_f32_e32 v66, 0xbfb8aa3b, v71
	v_rcp_f32_e32 v71, v67
	v_mul_f32_e32 v67, 0xbfb8aa3b, v72
	v_rcp_f32_e32 v72, v68
	v_mul_f32_e32 v68, 0xbfb8aa3b, v73
	v_exp_f32_e32 v70, v70
	v_exp_f32_e32 v66, v66
	v_exp_f32_e32 v67, v67
	v_exp_f32_e32 v68, v68
	v_exp_f32_e32 v69, v69
	v_add_f32_e32 v70, 1.0, v70
	v_add_f32_e32 v66, 1.0, v66
	v_add_f32_e32 v67, 1.0, v67
	v_add_f32_e32 v68, 1.0, v68
	v_add_f32_e32 v69, 1.0, v69
	v_rcp_f32_e32 v70, v70
	v_rcp_f32_e32 v66, v66
	v_rcp_f32_e32 v67, v67
	v_rcp_f32_e32 v68, v68
	v_rcp_f32_e32 v69, v69
	s_or_b32 s12, s44, 11
	s_ashr_i32 s13, s12, 31
	s_lshl_b64 s[12:13], s[12:13], 13
	v_cvt_pk_bf16_f32 v66, v70, v66
	v_cvt_pk_bf16_f32 v67, v67, v68
	v_cvt_pk_bf16_f32 v68, v74, v71
	v_cvt_pk_bf16_f32 v69, v72, v69
	v_lshl_add_u64 v[70:71], v[146:147], 0, s[12:13]
	global_store_dwordx4 v[70:71], v[66:69], off
	global_load_dwordx4 v[66:69], v[152:153], off offset:528
	s_nop 0
	global_load_dwordx4 v[70:73], v[152:153], off offset:512
	s_or_b32 s12, s44, 4
	s_ashr_i32 s13, s12, 31
	s_lshl_b64 s[12:13], s[12:13], 13
	s_waitcnt vmcnt(1)
	v_pk_add_f32 v[60:61], v[60:61], v[68:69]
	v_pk_add_f32 v[58:59], v[58:59], v[66:67]
	v_mul_f32_e32 v60, 0xbfb8aa3b, v60
	v_mul_f32_e32 v58, 0xbfb8aa3b, v58
	v_mul_f32_e32 v59, 0xbfb8aa3b, v59
	v_exp_f32_e32 v58, v58
	v_exp_f32_e32 v59, v59
	v_exp_f32_e32 v60, v60
	s_waitcnt vmcnt(0)
; __device__ __forceinline__ unsigned cvt_pk_bf16(float lo, float hi) { const f32x2 v = {lo, hi}; const bf16x2_t b = __builtin_convertvector(v, bf16x2_t); return __builtin_bit_cast(unsigned, b); }
; __device__ __forceinline__ float fast_sigmoid(float x) { return __builtin_amdgcn_rcpf(1.0f + __builtin_amdgcn_exp2f(-x * LOG2E)); }
;     __device__ __forceinline__ void operator()(const f32x4 (&acc)[2][2][4][2], const Unit& u, int wr, int wc, int fr, int fq) const {
;     ...
;         if ((u.j & 1) == 0) {
; #pragma unroll
;             for (int bj = 0; bj < 2; ++bj) { const f32x4 b0 = *(const f32x4*)(bgate + br * 1024 + col00 + bj * 128), b1 = *(const f32x4*)(bgate + br * 1024 + col00 + bj * 128 + 4);
; #pragma unroll
;                 for (int ai = 0; ai < 2; ++ai)
; #pragma unroll
;                     for (int m = 0; m < 4; ++m) { f32x4 v0 = acc[ai][bj][m][0] + b0, v1 = acc[ai][bj][m][1] + b1;
; #pragma unroll
;                         for (int i = 0; i < 4; ++i) { v0[i] = fast_sigmoid(v0[i]); v1[i] = fast_sigmoid(v1[i]); }
;                         u32x4 w; w.x = cvt_pk_bf16(v0[0], v0[1]); w.y = cvt_pk_bf16(v0[2], v0[3]); w.z = cvt_pk_bf16(v1[0], v1[1]); w.w = cvt_pk_bf16(v1[2], v1[3]);
;                         *((u32x4*)Gs + ((size_t)(tile * 16 + (ai * 2 + bj) * 4 + m) * NTHREADS + tid)) = w; } }
	v_pk_add_f32 v[64:65], v[64:65], v[72:73]
	v_pk_add_f32 v[62:63], v[62:63], v[70:71]
	v_add_f32_e32 v58, 1.0, v58
	v_add_f32_e32 v59, 1.0, v59
	v_add_f32_e32 v60, 1.0, v60
	v_mul_f32_e32 v62, 0xbfb8aa3b, v62
	v_rcp_f32_e32 v74, v58
	v_mul_f32_e32 v58, 0xbfb8aa3b, v63
	v_rcp_f32_e32 v63, v59
	v_mul_f32_e32 v59, 0xbfb8aa3b, v64
	v_rcp_f32_e32 v64, v60
	v_mul_f32_e32 v60, 0xbfb8aa3b, v65
	v_mul_f32_e32 v61, 0xbfb8aa3b, v61
	v_exp_f32_e32 v62, v62
	v_exp_f32_e32 v58, v58
	v_exp_f32_e32 v59, v59
	v_exp_f32_e32 v60, v60
	v_exp_f32_e32 v61, v61
	v_pk_add_f32 v[52:53], v[52:53], v[68:69]
	v_pk_add_f32 v[50:51], v[50:51], v[66:67]
	v_add_f32_e32 v62, 1.0, v62
	v_add_f32_e32 v58, 1.0, v58
	v_add_f32_e32 v59, 1.0, v59
	v_add_f32_e32 v60, 1.0, v60
	v_add_f32_e32 v61, 1.0, v61
	v_mul_f32_e32 v50, 0xbfb8aa3b, v50
	v_mul_f32_e32 v51, 0xbfb8aa3b, v51
	v_mul_f32_e32 v52, 0xbfb8aa3b, v52
	v_rcp_f32_e32 v62, v62
	v_rcp_f32_e32 v58, v58
	v_rcp_f32_e32 v59, v59
	v_rcp_f32_e32 v60, v60
	v_rcp_f32_e32 v61, v61
	v_exp_f32_e32 v50, v50
	v_exp_f32_e32 v51, v51
	v_exp_f32_e32 v52, v52
	v_cvt_pk_bf16_f32 v58, v62, v58
	v_cvt_pk_bf16_f32 v59, v59, v60
	v_cvt_pk_bf16_f32 v60, v74, v63
	v_cvt_pk_bf16_f32 v61, v64, v61
	v_lshl_add_u64 v[62:63], v[146:147], 0, s[12:13]
	v_pk_add_f32 v[56:57], v[56:57], v[72:73]
	v_pk_add_f32 v[54:55], v[54:55], v[70:71]
	v_add_f32_e32 v50, 1.0, v50
	v_add_f32_e32 v51, 1.0, v51
	v_add_f32_e32 v52, 1.0, v52
	v_mov_b32_e32 v246, v58
	v_mov_b32_e32 v247, v59
	v_mov_b32_e32 v248, v60
	v_mov_b32_e32 v249, v61
	v_mul_f32_e32 v54, 0xbfb8aa3b, v54
	v_mul_f32_e32 v53, 0xbfb8aa3b, v53
	v_rcp_f32_e32 v58, v50
	v_mul_f32_e32 v50, 0xbfb8aa3b, v55
	v_rcp_f32_e32 v55, v51
	v_mul_f32_e32 v51, 0xbfb8aa3b, v56
	v_rcp_f32_e32 v56, v52
	v_mul_f32_e32 v52, 0xbfb8aa3b, v57
	v_exp_f32_e32 v54, v54
	v_exp_f32_e32 v50, v50
	v_exp_f32_e32 v51, v51
	v_exp_f32_e32 v52, v52
	v_exp_f32_e32 v53, v53
	v_pk_add_f32 v[44:45], v[44:45], v[68:69]
	v_pk_add_f32 v[42:43], v[42:43], v[66:67]
	v_add_f32_e32 v54, 1.0, v54
	v_add_f32_e32 v50, 1.0, v50
	v_add_f32_e32 v51, 1.0, v51
	v_add_f32_e32 v52, 1.0, v52
	v_add_f32_e32 v53, 1.0, v53
	v_mul_f32_e32 v42, 0xbfb8aa3b, v42
	v_mul_f32_e32 v43, 0xbfb8aa3b, v43
	v_mul_f32_e32 v44, 0xbfb8aa3b, v44
	v_rcp_f32_e32 v54, v54
	v_rcp_f32_e32 v50, v50
	v_rcp_f32_e32 v51, v51
	v_rcp_f32_e32 v52, v52
	v_rcp_f32_e32 v53, v53
	v_exp_f32_e32 v42, v42
	v_exp_f32_e32 v43, v43
	v_exp_f32_e32 v44, v44
	s_or_b32 s12, s44, 5
	s_ashr_i32 s13, s12, 31
	s_lshl_b64 s[12:13], s[12:13], 13
	v_cvt_pk_bf16_f32 v50, v54, v50
	v_cvt_pk_bf16_f32 v51, v51, v52
	v_cvt_pk_bf16_f32 v52, v58, v55
	v_cvt_pk_bf16_f32 v53, v56, v53
	v_lshl_add_u64 v[54:55], v[146:147], 0, s[12:13]
	v_pk_add_f32 v[48:49], v[48:49], v[72:73]
	v_pk_add_f32 v[46:47], v[46:47], v[70:71]
	v_add_f32_e32 v42, 1.0, v42
	v_add_f32_e32 v43, 1.0, v43
	v_add_f32_e32 v44, 1.0, v44
	v_mov_b32_e32 v198, v50
	v_mov_b32_e32 v199, v51
	v_mov_b32_e32 v200, v52
	v_mov_b32_e32 v201, v53
	v_mul_f32_e32 v46, 0xbfb8aa3b, v46
	v_mul_f32_e32 v45, 0xbfb8aa3b, v45
	v_rcp_f32_e32 v50, v42
	v_mul_f32_e32 v42, 0xbfb8aa3b, v47
	v_rcp_f32_e32 v47, v43
	v_mul_f32_e32 v43, 0xbfb8aa3b, v48
	v_rcp_f32_e32 v48, v44
	v_mul_f32_e32 v44, 0xbfb8aa3b, v49
	v_exp_f32_e32 v46, v46
	v_exp_f32_e32 v42, v42
	v_exp_f32_e32 v43, v43
	v_exp_f32_e32 v44, v44
	v_exp_f32_e32 v45, v45
	v_pk_add_f32 v[36:37], v[36:37], v[68:69]
	v_pk_add_f32 v[34:35], v[34:35], v[66:67]
	v_add_f32_e32 v46, 1.0, v46
	v_add_f32_e32 v42, 1.0, v42
	v_add_f32_e32 v43, 1.0, v43
	v_add_f32_e32 v44, 1.0, v44
	v_add_f32_e32 v45, 1.0, v45
	v_mul_f32_e32 v34, 0xbfb8aa3b, v34
	v_mul_f32_e32 v35, 0xbfb8aa3b, v35
	v_mul_f32_e32 v36, 0xbfb8aa3b, v36
	v_rcp_f32_e32 v46, v46
	v_rcp_f32_e32 v42, v42
	v_rcp_f32_e32 v43, v43
	v_rcp_f32_e32 v44, v44
	v_rcp_f32_e32 v45, v45
	v_exp_f32_e32 v34, v34
	v_exp_f32_e32 v35, v35
	v_exp_f32_e32 v36, v36
	s_or_b32 s12, s44, 6
	s_ashr_i32 s13, s12, 31
	s_lshl_b64 s[12:13], s[12:13], 13
	v_cvt_pk_bf16_f32 v42, v46, v42
	v_cvt_pk_bf16_f32 v43, v43, v44
	v_cvt_pk_bf16_f32 v44, v50, v47
	v_cvt_pk_bf16_f32 v45, v48, v45
	v_lshl_add_u64 v[46:47], v[146:147], 0, s[12:13]
	v_pk_add_f32 v[40:41], v[40:41], v[72:73]
	v_pk_add_f32 v[38:39], v[38:39], v[70:71]
	v_add_f32_e32 v34, 1.0, v34
	v_add_f32_e32 v35, 1.0, v35
	v_add_f32_e32 v36, 1.0, v36
	global_store_dwordx4 v[46:47], v[42:45], off
	v_mul_f32_e32 v38, 0xbfb8aa3b, v38
	v_mul_f32_e32 v37, 0xbfb8aa3b, v37
	v_rcp_f32_e32 v42, v34
	v_mul_f32_e32 v34, 0xbfb8aa3b, v39
	v_rcp_f32_e32 v39, v35
	v_mul_f32_e32 v35, 0xbfb8aa3b, v40
	v_rcp_f32_e32 v40, v36
	v_mul_f32_e32 v36, 0xbfb8aa3b, v41
	v_exp_f32_e32 v38, v38
	v_exp_f32_e32 v34, v34
	v_exp_f32_e32 v35, v35
	v_exp_f32_e32 v36, v36
	v_exp_f32_e32 v37, v37
	v_pk_add_f32 v[28:29], v[28:29], v[68:69]
	v_pk_add_f32 v[26:27], v[26:27], v[66:67]
	v_add_f32_e32 v38, 1.0, v38
	v_add_f32_e32 v34, 1.0, v34
	v_add_f32_e32 v35, 1.0, v35
	v_add_f32_e32 v36, 1.0, v36
	v_add_f32_e32 v37, 1.0, v37
	v_mul_f32_e32 v26, 0xbfb8aa3b, v26
	v_mul_f32_e32 v27, 0xbfb8aa3b, v27
	v_mul_f32_e32 v28, 0xbfb8aa3b, v28
	v_rcp_f32_e32 v38, v38
	v_rcp_f32_e32 v34, v34
	v_rcp_f32_e32 v35, v35
	v_rcp_f32_e32 v36, v36
	v_rcp_f32_e32 v37, v37
	v_exp_f32_e32 v26, v26
	v_exp_f32_e32 v27, v27
	v_exp_f32_e32 v28, v28
	s_or_b32 s12, s44, 7
	s_ashr_i32 s13, s12, 31
	s_lshl_b64 s[12:13], s[12:13], 13
	v_cvt_pk_bf16_f32 v34, v38, v34
	v_cvt_pk_bf16_f32 v35, v35, v36
; __device__ __forceinline__ unsigned cvt_pk_bf16(float lo, float hi) { const f32x2 v = {lo, hi}; const bf16x2_t b = __builtin_convertvector(v, bf16x2_t); return __builtin_bit_cast(unsigned, b); }
; __device__ __forceinline__ float fast_sigmoid(float x) { return __builtin_amdgcn_rcpf(1.0f + __builtin_amdgcn_exp2f(-x * LOG2E)); }
;     __device__ __forceinline__ void operator()(const f32x4 (&acc)[2][2][4][2], const Unit& u, int wr, int wc, int fr, int fq) const {
;     ...
;         if ((u.j & 1) == 0) {
; #pragma unroll
;             for (int bj = 0; bj < 2; ++bj) { const f32x4 b0 = *(const f32x4*)(bgate + br * 1024 + col00 + bj * 128), b1 = *(const f32x4*)(bgate + br * 1024 + col00 + bj * 128 + 4);
; #pragma unroll
;                 for (int ai = 0; ai < 2; ++ai)
; #pragma unroll
;                     for (int m = 0; m < 4; ++m) { f32x4 v0 = acc[ai][bj][m][0] + b0, v1 = acc[ai][bj][m][1] + b1;
; #pragma unroll
;                         for (int i = 0; i < 4; ++i) { v0[i] = fast_sigmoid(v0[i]); v1[i] = fast_sigmoid(v1[i]); }
;                         u32x4 w; w.x = cvt_pk_bf16(v0[0], v0[1]); w.y = cvt_pk_bf16(v0[2], v0[3]); w.z = cvt_pk_bf16(v1[0], v1[1]); w.w = cvt_pk_bf16(v1[2], v1[3]);
;                         *((u32x4*)Gs + ((size_t)(tile * 16 + (ai * 2 + bj) * 4 + m) * NTHREADS + tid)) = w; } }
	v_cvt_pk_bf16_f32 v36, v42, v39
	v_cvt_pk_bf16_f32 v37, v40, v37
	v_lshl_add_u64 v[38:39], v[146:147], 0, s[12:13]
	v_pk_add_f32 v[32:33], v[32:33], v[72:73]
	v_pk_add_f32 v[30:31], v[30:31], v[70:71]
	v_add_f32_e32 v26, 1.0, v26
	v_add_f32_e32 v27, 1.0, v27
	v_add_f32_e32 v28, 1.0, v28
	global_store_dwordx4 v[38:39], v[34:37], off
	v_mul_f32_e32 v30, 0xbfb8aa3b, v30
	v_mul_f32_e32 v29, 0xbfb8aa3b, v29
	v_rcp_f32_e32 v34, v26
	v_mul_f32_e32 v26, 0xbfb8aa3b, v31
	v_rcp_f32_e32 v31, v27
	v_mul_f32_e32 v27, 0xbfb8aa3b, v32
	v_rcp_f32_e32 v32, v28
	v_mul_f32_e32 v28, 0xbfb8aa3b, v33
	v_exp_f32_e32 v30, v30
	v_exp_f32_e32 v26, v26
	v_exp_f32_e32 v27, v27
	v_exp_f32_e32 v28, v28
	v_exp_f32_e32 v29, v29
	v_pk_add_f32 v[20:21], v[20:21], v[68:69]
	v_pk_add_f32 v[18:19], v[18:19], v[66:67]
	v_add_f32_e32 v30, 1.0, v30
	v_add_f32_e32 v26, 1.0, v26
	v_add_f32_e32 v27, 1.0, v27
	v_add_f32_e32 v28, 1.0, v28
	v_add_f32_e32 v29, 1.0, v29
	v_mul_f32_e32 v18, 0xbfb8aa3b, v18
	v_mul_f32_e32 v19, 0xbfb8aa3b, v19
	v_mul_f32_e32 v20, 0xbfb8aa3b, v20
	v_rcp_f32_e32 v30, v30
	v_rcp_f32_e32 v26, v26
	v_rcp_f32_e32 v27, v27
	v_rcp_f32_e32 v28, v28
	v_rcp_f32_e32 v29, v29
	v_exp_f32_e32 v18, v18
	v_exp_f32_e32 v19, v19
	v_exp_f32_e32 v20, v20
	s_or_b32 s12, s44, 12
	s_ashr_i32 s13, s12, 31
	s_lshl_b64 s[12:13], s[12:13], 13
	v_cvt_pk_bf16_f32 v26, v30, v26
	v_cvt_pk_bf16_f32 v27, v27, v28
	v_cvt_pk_bf16_f32 v28, v34, v31
	v_cvt_pk_bf16_f32 v29, v32, v29
	v_lshl_add_u64 v[30:31], v[146:147], 0, s[12:13]
	v_pk_add_f32 v[24:25], v[24:25], v[72:73]
	v_pk_add_f32 v[22:23], v[22:23], v[70:71]
	v_add_f32_e32 v18, 1.0, v18
	v_add_f32_e32 v19, 1.0, v19
	v_add_f32_e32 v20, 1.0, v20
	global_store_dwordx4 v[30:31], v[26:29], off
	v_mul_f32_e32 v22, 0xbfb8aa3b, v22
	v_mul_f32_e32 v21, 0xbfb8aa3b, v21
	v_rcp_f32_e32 v26, v18
	v_mul_f32_e32 v18, 0xbfb8aa3b, v23
	v_rcp_f32_e32 v23, v19
	v_mul_f32_e32 v19, 0xbfb8aa3b, v24
	v_rcp_f32_e32 v24, v20
	v_mul_f32_e32 v20, 0xbfb8aa3b, v25
	v_exp_f32_e32 v22, v22
	v_exp_f32_e32 v18, v18
	v_exp_f32_e32 v19, v19
	v_exp_f32_e32 v20, v20
	v_exp_f32_e32 v21, v21
	v_pk_add_f32 v[12:13], v[12:13], v[68:69]
	v_pk_add_f32 v[10:11], v[10:11], v[66:67]
	v_add_f32_e32 v22, 1.0, v22
	v_add_f32_e32 v18, 1.0, v18
	v_add_f32_e32 v19, 1.0, v19
	v_add_f32_e32 v20, 1.0, v20
	v_add_f32_e32 v21, 1.0, v21
	v_mul_f32_e32 v10, 0xbfb8aa3b, v10
	v_mul_f32_e32 v11, 0xbfb8aa3b, v11
	v_mul_f32_e32 v12, 0xbfb8aa3b, v12
	v_rcp_f32_e32 v22, v22
	v_rcp_f32_e32 v18, v18
	v_rcp_f32_e32 v19, v19
	v_rcp_f32_e32 v20, v20
	v_rcp_f32_e32 v21, v21
	v_exp_f32_e32 v10, v10
	v_exp_f32_e32 v11, v11
	v_exp_f32_e32 v12, v12
	s_or_b32 s12, s44, 13
	s_ashr_i32 s13, s12, 31
	s_lshl_b64 s[12:13], s[12:13], 13
	v_cvt_pk_bf16_f32 v18, v22, v18
	v_cvt_pk_bf16_f32 v19, v19, v20
	v_cvt_pk_bf16_f32 v20, v26, v23
	v_cvt_pk_bf16_f32 v21, v24, v21
	v_lshl_add_u64 v[22:23], v[146:147], 0, s[12:13]
	v_pk_add_f32 v[16:17], v[16:17], v[72:73]
	v_pk_add_f32 v[14:15], v[14:15], v[70:71]
	v_add_f32_e32 v10, 1.0, v10
	v_add_f32_e32 v11, 1.0, v11
	v_add_f32_e32 v12, 1.0, v12
	global_store_dwordx4 v[22:23], v[18:21], off
	v_mul_f32_e32 v14, 0xbfb8aa3b, v14
	v_mul_f32_e32 v13, 0xbfb8aa3b, v13
	v_rcp_f32_e32 v18, v10
	v_mul_f32_e32 v10, 0xbfb8aa3b, v15
	v_rcp_f32_e32 v15, v11
	v_mul_f32_e32 v11, 0xbfb8aa3b, v16
	v_rcp_f32_e32 v16, v12
	v_mul_f32_e32 v12, 0xbfb8aa3b, v17
	v_exp_f32_e32 v14, v14
	v_exp_f32_e32 v10, v10
	v_exp_f32_e32 v11, v11
	v_exp_f32_e32 v12, v12
	v_exp_f32_e32 v13, v13
	v_pk_add_f32 v[4:5], v[4:5], v[68:69]
	v_pk_add_f32 v[2:3], v[2:3], v[66:67]
	v_add_f32_e32 v14, 1.0, v14
	v_add_f32_e32 v10, 1.0, v10
	v_add_f32_e32 v11, 1.0, v11
	v_add_f32_e32 v12, 1.0, v12
	v_add_f32_e32 v13, 1.0, v13
	v_mul_f32_e32 v2, 0xbfb8aa3b, v2
	v_mul_f32_e32 v3, 0xbfb8aa3b, v3
	v_mul_f32_e32 v4, 0xbfb8aa3b, v4
	v_rcp_f32_e32 v14, v14
	v_rcp_f32_e32 v10, v10
	v_rcp_f32_e32 v11, v11
	v_rcp_f32_e32 v12, v12
	v_rcp_f32_e32 v13, v13
	v_exp_f32_e32 v2, v2
	v_exp_f32_e32 v3, v3
	v_exp_f32_e32 v4, v4
	s_or_b32 s12, s44, 14
	s_ashr_i32 s13, s12, 31
	s_lshl_b64 s[12:13], s[12:13], 13
	v_cvt_pk_bf16_f32 v10, v14, v10
	v_cvt_pk_bf16_f32 v11, v11, v12
	v_cvt_pk_bf16_f32 v12, v18, v15
	v_cvt_pk_bf16_f32 v13, v16, v13
	v_lshl_add_u64 v[14:15], v[146:147], 0, s[12:13]
	v_pk_add_f32 v[8:9], v[8:9], v[72:73]
	v_pk_add_f32 v[6:7], v[6:7], v[70:71]
	v_add_f32_e32 v2, 1.0, v2
	v_add_f32_e32 v3, 1.0, v3
	v_add_f32_e32 v4, 1.0, v4
	global_store_dwordx4 v[14:15], v[10:13], off
	v_mul_f32_e32 v6, 0xbfb8aa3b, v6
	v_mul_f32_e32 v5, 0xbfb8aa3b, v5
	v_rcp_f32_e32 v10, v2
	v_mul_f32_e32 v2, 0xbfb8aa3b, v7
	v_rcp_f32_e32 v7, v3
	v_mul_f32_e32 v3, 0xbfb8aa3b, v8
	v_rcp_f32_e32 v8, v4
	v_mul_f32_e32 v4, 0xbfb8aa3b, v9
	v_exp_f32_e32 v6, v6
	v_exp_f32_e32 v2, v2
	v_exp_f32_e32 v3, v3
	v_exp_f32_e32 v4, v4
	v_exp_f32_e32 v5, v5
	v_add_f32_e32 v6, 1.0, v6
	v_add_f32_e32 v2, 1.0, v2
	v_add_f32_e32 v3, 1.0, v3
	v_add_f32_e32 v4, 1.0, v4
	v_add_f32_e32 v5, 1.0, v5
	v_rcp_f32_e32 v6, v6
	v_rcp_f32_e32 v2, v2
	v_rcp_f32_e32 v3, v3
	v_rcp_f32_e32 v4, v4
	v_rcp_f32_e32 v5, v5
	s_or_b32 s12, s44, 15
	s_ashr_i32 s13, s12, 31
	s_lshl_b64 s[12:13], s[12:13], 13
	v_cvt_pk_bf16_f32 v2, v6, v2
	v_cvt_pk_bf16_f32 v3, v3, v4
	v_cvt_pk_bf16_f32 v4, v10, v7
	v_cvt_pk_bf16_f32 v5, v8, v5
	v_lshl_add_u64 v[6:7], v[146:147], 0, s[12:13]
	global_store_dwordx4 v[6:7], v[2:5], off
	s_and_b64 vcc, exec, s[42:43]
	s_mov_b64 s[12:13], -1
	s_cbranch_vccnz .LBB0_283
